# tile boundary of the peeled GEMM loops: the first segment's 12 fragment ds_reads are issued at the tile-loop head, ahead of the scalar next-tile coordinate math
# speedup vs baseline: 1.0125x; 1.0051x over previous
.LBB0_51:
	v_add_u32_e32 v194, 0x10000, v143
	ds_read_b128 v[146:149], v194
	ds_read_b128 v[150:153], v194 offset:1024
	ds_read_b128 v[154:157], v194 offset:2048
	ds_read_b128 v[158:161], v194 offset:3072
	ds_read_b128 v[162:165], v144
	ds_read_b128 v[166:169], v144 offset:1024
	ds_read_b128 v[170:173], v144 offset:2048
	ds_read_b128 v[174:177], v144 offset:3072
	ds_read_b128 v[178:181], v144 offset:4096
	ds_read_b128 v[182:185], v144 offset:5120
	ds_read_b128 v[186:189], v144 offset:6144
	ds_read_b128 v[190:193], v144 offset:7168
	s_add_i32 s58, s58, 1
	s_mul_i32 s20, s58, s51
	s_mul_hi_u32 s21, s58, s30
	s_add_i32 s21, s21, s20
	s_mul_i32 s20, s58, s30
	s_add_u32 s46, s20, s31
	s_addc_u32 s47, s21, s50
	v_mov_b64_e32 v[4:5], 0x1ff
	v_cmp_gt_i64_e64 s[38:39], s[46:47], v[4:5]
	s_and_b64 vcc, exec, s[38:39]
	s_cbranch_vccnz .LBB0_57
	s_ashr_i32 s0, s46, 31
	s_lshr_b32 s0, s0, 29
	s_add_i32 s20, s46, s0
	s_and_b32 s0, s20, -8
	s_sub_i32 s21, s46, s0
	s_cmp_gt_i32 s21, -1
	s_mov_b64 s[0:1], -1
	s_cbranch_scc0 .LBB0_54
	s_lshl_b32 s22, s21, 6
	s_mov_b64 s[0:1], 0

.LBB0_57:
	s_add_u32 s20, s44, 0x100
	s_addc_u32 s21, s45, 0
	s_mov_b32 s22, -2
	s_add_u32 s44, s42, 0x100
	s_addc_u32 s45, s43, 0
	s_add_i32 s23, 0, 0x10000
	s_add_i32 m0, s52, 0xc000
	s_cmp_eq_u32 s22, 40
	s_cselect_b32 s49, s1, s45
	s_cselect_b32 s48, s0, s44
	s_cselect_b32 s47, s41, s21
	s_cselect_b32 s46, s40, s20
	global_load_lds_dwordx4 v138, s[42:43]
	s_add_i32 m0, s52, 0xe000
	s_nop 0
	global_load_lds_dwordx4 v140, s[42:43]
	s_waitcnt lgkmcnt(8)
	s_barrier
	s_waitcnt lgkmcnt(0)
	v_mfma_f32_16x16x32_bf16 v[128:131], v[146:149], v[162:165], 0
	v_mfma_f32_16x16x32_bf16 v[124:127], v[154:157], v[162:165], 0
	v_mfma_f32_16x16x32_bf16 v[120:123], v[146:149], v[170:173], 0
	v_mfma_f32_16x16x32_bf16 v[116:119], v[154:157], v[170:173], 0
	v_mfma_f32_16x16x32_bf16 v[104:107], v[146:149], v[178:181], 0
	v_mfma_f32_16x16x32_bf16 v[100:103], v[154:157], v[178:181], 0
	v_mfma_f32_16x16x32_bf16 v[88:91], v[146:149], v[186:189], 0
	v_mfma_f32_16x16x32_bf16 v[84:87], v[154:157], v[186:189], 0
	v_mfma_f32_16x16x32_bf16 v[128:131], v[150:153], v[166:169], v[128:131]
	v_mfma_f32_16x16x32_bf16 v[124:127], v[158:161], v[166:169], v[124:127]
	v_mfma_f32_16x16x32_bf16 v[120:123], v[150:153], v[174:177], v[120:123]
	v_mfma_f32_16x16x32_bf16 v[116:119], v[158:161], v[174:177], v[116:119]
	v_mfma_f32_16x16x32_bf16 v[104:107], v[150:153], v[182:185], v[104:107]
	v_mfma_f32_16x16x32_bf16 v[100:103], v[158:161], v[182:185], v[100:103]
	v_mfma_f32_16x16x32_bf16 v[88:91], v[150:153], v[190:193], v[88:91]
	v_mfma_f32_16x16x32_bf16 v[84:87], v[158:161], v[190:193], v[84:87]
	s_barrier
	s_add_i32 s26, 0, 0x14000
	s_add_i32 s23, s23, s37
	s_mov_b32 m0, s23
	ds_read_b128 v[202:205], v194 offset:16384
	ds_read_b128 v[206:209], v194 offset:17408
	ds_read_b128 v[210:213], v194 offset:18432
	global_load_lds_dwordx4 v132, s[46:47]
	s_add_i32 m0, s23, 0x2000
	ds_read_b128 v[214:217], v194 offset:19456
	global_load_lds_dwordx4 v136, s[46:47]
	s_barrier
	s_waitcnt lgkmcnt(0)
	v_mfma_f32_16x16x32_bf16 v[112:115], v[202:205], v[162:165], 0
	v_mfma_f32_16x16x32_bf16 v[108:111], v[210:213], v[162:165], 0
	v_mfma_f32_16x16x32_bf16 v[96:99], v[202:205], v[170:173], 0
	v_mfma_f32_16x16x32_bf16 v[92:95], v[210:213], v[170:173], 0
	v_mfma_f32_16x16x32_bf16 v[80:83], v[202:205], v[178:181], 0
	v_mfma_f32_16x16x32_bf16 v[76:79], v[210:213], v[178:181], 0
	v_mfma_f32_16x16x32_bf16 v[72:75], v[202:205], v[186:189], 0
	v_mfma_f32_16x16x32_bf16 v[68:71], v[210:213], v[186:189], 0
	v_mfma_f32_16x16x32_bf16 v[112:115], v[206:209], v[166:169], v[112:115]
	v_mfma_f32_16x16x32_bf16 v[108:111], v[214:217], v[166:169], v[108:111]
	v_mfma_f32_16x16x32_bf16 v[96:99], v[206:209], v[174:177], v[96:99]
	v_mfma_f32_16x16x32_bf16 v[92:95], v[214:217], v[174:177], v[92:95]
	v_mfma_f32_16x16x32_bf16 v[80:83], v[206:209], v[182:185], v[80:83]
	v_mfma_f32_16x16x32_bf16 v[76:79], v[214:217], v[182:185], v[76:79]
	v_mfma_f32_16x16x32_bf16 v[72:75], v[206:209], v[190:193], v[72:75]
	v_mfma_f32_16x16x32_bf16 v[68:71], v[214:217], v[190:193], v[68:71]
	s_mov_b32 m0, s52
	s_barrier
	ds_read_b128 v[162:165], v144 offset:16384
	ds_read_b128 v[166:169], v144 offset:17408
	ds_read_b128 v[170:173], v144 offset:18432
	ds_read_b128 v[174:177], v144 offset:19456
	ds_read_b128 v[178:181], v144 offset:20480
	ds_read_b128 v[182:185], v144 offset:21504
	ds_read_b128 v[186:189], v144 offset:22528
	global_load_lds_dwordx4 v0, s[48:49]
	s_mov_b32 m0, s53
	ds_read_b128 v[190:193], v144 offset:23552
	global_load_lds_dwordx4 v134, s[48:49]
	s_barrier
	s_waitcnt lgkmcnt(0)
	v_mfma_f32_16x16x32_bf16 v[64:67], v[146:149], v[162:165], 0
	v_mfma_f32_16x16x32_bf16 v[60:63], v[154:157], v[162:165], 0
	v_mfma_f32_16x16x32_bf16 v[56:59], v[146:149], v[170:173], 0
	v_mfma_f32_16x16x32_bf16 v[52:55], v[154:157], v[170:173], 0
	v_mfma_f32_16x16x32_bf16 v[40:43], v[146:149], v[178:181], 0
	v_mfma_f32_16x16x32_bf16 v[36:39], v[154:157], v[178:181], 0
	v_mfma_f32_16x16x32_bf16 v[24:27], v[146:149], v[186:189], 0
	v_mfma_f32_16x16x32_bf16 v[16:19], v[154:157], v[186:189], 0
	v_mfma_f32_16x16x32_bf16 v[64:67], v[150:153], v[166:169], v[64:67]
	v_mfma_f32_16x16x32_bf16 v[60:63], v[158:161], v[166:169], v[60:63]
	v_mfma_f32_16x16x32_bf16 v[56:59], v[150:153], v[174:177], v[56:59]
	v_mfma_f32_16x16x32_bf16 v[52:55], v[158:161], v[174:177], v[52:55]
	v_mfma_f32_16x16x32_bf16 v[40:43], v[150:153], v[182:185], v[40:43]
	v_mfma_f32_16x16x32_bf16 v[36:39], v[158:161], v[182:185], v[36:39]
	v_mfma_f32_16x16x32_bf16 v[24:27], v[150:153], v[190:193], v[24:27]
	v_mfma_f32_16x16x32_bf16 v[16:19], v[158:161], v[190:193], v[16:19]
	s_barrier
	s_add_i32 s23, s26, s37
	s_mov_b32 m0, s23
	s_add_u32 s24, s46, 0xb0000
	s_addc_u32 s25, s47, 0
	global_load_lds_dwordx4 v132, s[24:25]
	s_add_i32 m0, s23, 0x2000
	s_waitcnt vmcnt(5)
	global_load_lds_dwordx4 v136, s[24:25]
	s_barrier
	v_mfma_f32_16x16x32_bf16 v[48:51], v[202:205], v[162:165], 0
	v_mfma_f32_16x16x32_bf16 v[44:47], v[210:213], v[162:165], 0
	v_mfma_f32_16x16x32_bf16 v[32:35], v[202:205], v[170:173], 0
	v_mfma_f32_16x16x32_bf16 v[28:31], v[210:213], v[170:173], 0
	v_mfma_f32_16x16x32_bf16 v[20:23], v[202:205], v[178:181], 0
	v_mfma_f32_16x16x32_bf16 v[12:15], v[210:213], v[178:181], 0
	v_mfma_f32_16x16x32_bf16 v[8:11], v[202:205], v[186:189], 0
	v_mfma_f32_16x16x32_bf16 v[4:7], v[210:213], v[186:189], 0
	v_mfma_f32_16x16x32_bf16 v[48:51], v[206:209], v[166:169], v[48:51]
	v_mfma_f32_16x16x32_bf16 v[44:47], v[214:217], v[166:169], v[44:47]
	v_mfma_f32_16x16x32_bf16 v[32:35], v[206:209], v[174:177], v[32:35]
	v_mfma_f32_16x16x32_bf16 v[28:31], v[214:217], v[174:177], v[28:31]
	v_mfma_f32_16x16x32_bf16 v[20:23], v[206:209], v[182:185], v[20:23]
	v_mfma_f32_16x16x32_bf16 v[12:15], v[214:217], v[182:185], v[12:15]
	v_mfma_f32_16x16x32_bf16 v[8:11], v[206:209], v[190:193], v[8:11]
	v_mfma_f32_16x16x32_bf16 v[4:7], v[214:217], v[190:193], v[4:7]
	s_add_i32 s23, 0, 0x18000
	s_barrier
	ds_read_b128 v[146:149], v194 offset:32768
	ds_read_b128 v[150:153], v194 offset:33792
	ds_read_b128 v[154:157], v194 offset:34816
	ds_read_b128 v[158:161], v194 offset:35840
	s_add_u32 s24, s48, 0xb0000
	s_addc_u32 s25, s49, 0
	s_mov_b32 m0, s54
	ds_read_b128 v[162:165], v144 offset:32768
	ds_read_b128 v[166:169], v144 offset:33792
	ds_read_b128 v[170:173], v144 offset:34816
	ds_read_b128 v[174:177], v144 offset:35840
	ds_read_b128 v[178:181], v144 offset:36864
	ds_read_b128 v[182:185], v144 offset:37888
	ds_read_b128 v[186:189], v144 offset:38912
	global_load_lds_dwordx4 v0, s[24:25]
	s_mov_b32 m0, s55
	ds_read_b128 v[190:193], v144 offset:39936
	global_load_lds_dwordx4 v134, s[24:25]
	s_waitcnt lgkmcnt(8)
	s_barrier
	s_waitcnt lgkmcnt(0)
	v_mfma_f32_16x16x32_bf16 v[128:131], v[146:149], v[162:165], v[128:131]
	v_mfma_f32_16x16x32_bf16 v[124:127], v[154:157], v[162:165], v[124:127]
	v_mfma_f32_16x16x32_bf16 v[120:123], v[146:149], v[170:173], v[120:123]
	v_mfma_f32_16x16x32_bf16 v[116:119], v[154:157], v[170:173], v[116:119]
	v_mfma_f32_16x16x32_bf16 v[104:107], v[146:149], v[178:181], v[104:107]
	v_mfma_f32_16x16x32_bf16 v[100:103], v[154:157], v[178:181], v[100:103]
	v_mfma_f32_16x16x32_bf16 v[88:91], v[146:149], v[186:189], v[88:91]
	v_mfma_f32_16x16x32_bf16 v[84:87], v[154:157], v[186:189], v[84:87]
	v_mfma_f32_16x16x32_bf16 v[128:131], v[150:153], v[166:169], v[128:131]
	v_mfma_f32_16x16x32_bf16 v[124:127], v[158:161], v[166:169], v[124:127]
	v_mfma_f32_16x16x32_bf16 v[120:123], v[150:153], v[174:177], v[120:123]
	v_mfma_f32_16x16x32_bf16 v[116:119], v[158:161], v[174:177], v[116:119]
	v_mfma_f32_16x16x32_bf16 v[104:107], v[150:153], v[182:185], v[104:107]
	v_mfma_f32_16x16x32_bf16 v[100:103], v[158:161], v[182:185], v[100:103]
	v_mfma_f32_16x16x32_bf16 v[88:91], v[150:153], v[190:193], v[88:91]
	v_mfma_f32_16x16x32_bf16 v[84:87], v[158:161], v[190:193], v[84:87]
	s_barrier
	s_add_i32 s26, 0, 0x1c000
	s_add_i32 s23, s23, s37
	s_mov_b32 m0, s23
	ds_read_b128 v[202:205], v194 offset:49152
	ds_read_b128 v[206:209], v194 offset:50176
	ds_read_b128 v[210:213], v194 offset:51200
	s_add_u32 s98, s46, 0x80
	s_addc_u32 s99, s47, 0
	global_load_lds_dwordx4 v132, s[98:99]
	s_add_i32 m0, s23, 0x2000
	ds_read_b128 v[214:217], v194 offset:52224
	global_load_lds_dwordx4 v136, s[98:99]
	s_barrier
	s_waitcnt lgkmcnt(0)
	v_mfma_f32_16x16x32_bf16 v[112:115], v[202:205], v[162:165], v[112:115]
	v_mfma_f32_16x16x32_bf16 v[108:111], v[210:213], v[162:165], v[108:111]
	v_mfma_f32_16x16x32_bf16 v[96:99], v[202:205], v[170:173], v[96:99]
	v_mfma_f32_16x16x32_bf16 v[92:95], v[210:213], v[170:173], v[92:95]
	v_mfma_f32_16x16x32_bf16 v[80:83], v[202:205], v[178:181], v[80:83]
	v_mfma_f32_16x16x32_bf16 v[76:79], v[210:213], v[178:181], v[76:79]
	v_mfma_f32_16x16x32_bf16 v[72:75], v[202:205], v[186:189], v[72:75]
	v_mfma_f32_16x16x32_bf16 v[68:71], v[210:213], v[186:189], v[68:71]
	v_mfma_f32_16x16x32_bf16 v[112:115], v[206:209], v[166:169], v[112:115]
	v_mfma_f32_16x16x32_bf16 v[108:111], v[214:217], v[166:169], v[108:111]
	v_mfma_f32_16x16x32_bf16 v[96:99], v[206:209], v[174:177], v[96:99]
	v_mfma_f32_16x16x32_bf16 v[92:95], v[214:217], v[174:177], v[92:95]
	v_mfma_f32_16x16x32_bf16 v[80:83], v[206:209], v[182:185], v[80:83]
	v_mfma_f32_16x16x32_bf16 v[76:79], v[214:217], v[182:185], v[76:79]
	v_mfma_f32_16x16x32_bf16 v[72:75], v[206:209], v[190:193], v[72:75]
	v_mfma_f32_16x16x32_bf16 v[68:71], v[214:217], v[190:193], v[68:71]
	s_mov_b32 m0, s56
	s_barrier
	ds_read_b128 v[162:165], v144 offset:49152
	ds_read_b128 v[166:169], v144 offset:50176
	ds_read_b128 v[170:173], v144 offset:51200
	ds_read_b128 v[174:177], v144 offset:52224
	ds_read_b128 v[178:181], v144 offset:53248
	ds_read_b128 v[182:185], v144 offset:54272
	ds_read_b128 v[186:189], v144 offset:55296
	s_add_u32 s98, s48, 0x80
	s_addc_u32 s99, s49, 0
	global_load_lds_dwordx4 v0, s[98:99]
	s_mov_b32 m0, s57
	ds_read_b128 v[190:193], v144 offset:56320
	global_load_lds_dwordx4 v134, s[98:99]
	s_barrier
	s_waitcnt lgkmcnt(0)
	v_mfma_f32_16x16x32_bf16 v[64:67], v[146:149], v[162:165], v[64:67]
	v_mfma_f32_16x16x32_bf16 v[60:63], v[154:157], v[162:165], v[60:63]
	v_mfma_f32_16x16x32_bf16 v[56:59], v[146:149], v[170:173], v[56:59]
	v_mfma_f32_16x16x32_bf16 v[52:55], v[154:157], v[170:173], v[52:55]
	v_mfma_f32_16x16x32_bf16 v[40:43], v[146:149], v[178:181], v[40:43]
	v_mfma_f32_16x16x32_bf16 v[36:39], v[154:157], v[178:181], v[36:39]
	v_mfma_f32_16x16x32_bf16 v[24:27], v[146:149], v[186:189], v[24:27]
	v_mfma_f32_16x16x32_bf16 v[16:19], v[154:157], v[186:189], v[16:19]
	v_mfma_f32_16x16x32_bf16 v[64:67], v[150:153], v[166:169], v[64:67]
	v_mfma_f32_16x16x32_bf16 v[60:63], v[158:161], v[166:169], v[60:63]
	v_mfma_f32_16x16x32_bf16 v[56:59], v[150:153], v[174:177], v[56:59]
	v_mfma_f32_16x16x32_bf16 v[52:55], v[158:161], v[174:177], v[52:55]
	v_mfma_f32_16x16x32_bf16 v[40:43], v[150:153], v[182:185], v[40:43]
	v_mfma_f32_16x16x32_bf16 v[36:39], v[158:161], v[182:185], v[36:39]
	v_mfma_f32_16x16x32_bf16 v[24:27], v[150:153], v[190:193], v[24:27]
	v_mfma_f32_16x16x32_bf16 v[16:19], v[158:161], v[190:193], v[16:19]
	s_barrier
	s_add_i32 s23, s26, s37
	s_mov_b32 m0, s23
	s_add_u32 s24, s46, 0xb0080
	s_addc_u32 s25, s47, 0
	global_load_lds_dwordx4 v132, s[24:25]
	s_add_i32 m0, s23, 0x2000
	s_waitcnt vmcnt(5)
	global_load_lds_dwordx4 v136, s[24:25]
	s_barrier
	v_mfma_f32_16x16x32_bf16 v[48:51], v[202:205], v[162:165], v[48:51]
	v_mfma_f32_16x16x32_bf16 v[44:47], v[210:213], v[162:165], v[44:47]
	v_mfma_f32_16x16x32_bf16 v[32:35], v[202:205], v[170:173], v[32:35]
	v_mfma_f32_16x16x32_bf16 v[28:31], v[210:213], v[170:173], v[28:31]
	v_mfma_f32_16x16x32_bf16 v[20:23], v[202:205], v[178:181], v[20:23]
	v_mfma_f32_16x16x32_bf16 v[12:15], v[210:213], v[178:181], v[12:15]
	v_mfma_f32_16x16x32_bf16 v[8:11], v[202:205], v[186:189], v[8:11]
	v_mfma_f32_16x16x32_bf16 v[4:7], v[210:213], v[186:189], v[4:7]
	v_mfma_f32_16x16x32_bf16 v[48:51], v[206:209], v[166:169], v[48:51]
	v_mfma_f32_16x16x32_bf16 v[44:47], v[214:217], v[166:169], v[44:47]
	v_mfma_f32_16x16x32_bf16 v[32:35], v[206:209], v[174:177], v[32:35]
	v_mfma_f32_16x16x32_bf16 v[28:31], v[214:217], v[174:177], v[28:31]
	v_mfma_f32_16x16x32_bf16 v[20:23], v[206:209], v[182:185], v[20:23]
	v_mfma_f32_16x16x32_bf16 v[12:15], v[214:217], v[182:185], v[12:15]
	v_mfma_f32_16x16x32_bf16 v[8:11], v[206:209], v[190:193], v[8:11]
	v_mfma_f32_16x16x32_bf16 v[4:7], v[214:217], v[190:193], v[4:7]
	s_add_i32 s22, s22, 2
	s_add_u32 s20, s20, 0x100
	s_addc_u32 s21, s21, 0
	s_cmp_gt_u32 s22, 41
	s_mov_b64 s[42:43], s[44:45]
	s_barrier
	s_cbranch_scc1 .Lpeel_out_58

.LBB0_77:
	v_add_u32_e32 v198, 0x10000, v235
	ds_read_b128 v[52:55], v198
	ds_read_b128 v[56:59], v198 offset:1024
	ds_read_b128 v[60:63], v198 offset:2048
	ds_read_b128 v[64:67], v198 offset:3072
	ds_read_b128 v[76:79], v239
	ds_read_b128 v[80:83], v239 offset:1024
	ds_read_b128 v[84:87], v239 offset:2048
	ds_read_b128 v[88:91], v239 offset:3072
	ds_read_b128 v[92:95], v239 offset:4096
	ds_read_b128 v[96:99], v239 offset:5120
	ds_read_b128 v[100:103], v239 offset:6144
	ds_read_b128 v[104:107], v239 offset:7168
	s_add_i32 s75, s75, 1
	s_mul_i32 s1, s75, s80
	s_mul_hi_u32 s20, s75, s66
	s_add_i32 s20, s20, s1
	s_mul_i32 s1, s75, s66
	s_add_u32 s56, s1, s58
	s_addc_u32 s57, s20, s61
	v_mov_b64_e32 v[4:5], 0xaff
	v_cmp_gt_i64_e64 s[42:43], s[56:57], v[4:5]
	s_and_b64 vcc, exec, s[42:43]
	s_cbranch_vccnz .LBB0_79
	s_ashr_i32 s0, s56, 31
	s_lshr_b32 s0, s0, 29
	s_add_i32 s0, s56, s0
	s_ashr_i32 s1, s0, 3
	s_and_b32 s0, s0, -8
	s_sub_i32 s0, s56, s0
	s_cmp_lt_i32 s0, 0
	s_cselect_b32 s20, s4, 0x160
	s_mul_i32 s0, s20, s0
	s_add_i32 s0, s0, s1
	s_mul_hi_i32 s1, s0, 0x2e8ba2e9
	s_lshr_b32 s20, s1, 31
	s_ashr_i32 s1, s1, 5
	s_add_i32 s1, s1, s20
	s_lshl_b32 s20, s1, 3
	s_sub_i32 s21, 0x80, s20
	s_min_i32 s21, s21, 8
	s_abs_i32 s22, s21
	v_cvt_f32_u32_e32 v4, s22
	s_sub_i32 s24, 0, s22
	s_mulk_i32 s1, 0xb0
	s_sub_i32 s1, s0, s1
	v_rcp_iflag_f32_e32 v4, v4
	s_abs_i32 s0, s1
	s_xor_b32 s23, s1, s21
	s_ashr_i32 s23, s23, 31
	v_mul_f32_e32 v4, 0x4f7ffffe, v4
	v_cvt_u32_f32_e32 v4, v4
	s_nop 0
	v_readfirstlane_b32 s25, v4
	s_mul_i32 s24, s24, s25
	s_mul_hi_u32 s24, s25, s24
	s_add_i32 s25, s25, s24
	s_mul_hi_u32 s24, s0, s25
	s_mul_i32 s25, s24, s22
	s_sub_i32 s0, s0, s25
	s_add_i32 s26, s24, 1
	s_sub_i32 s25, s0, s22
	s_cmp_ge_u32 s0, s22
	s_cselect_b32 s24, s26, s24
	s_cselect_b32 s0, s25, s0
	s_add_i32 s25, s24, 1
	s_cmp_ge_u32 s0, s22
	s_cselect_b32 s0, s25, s24
	s_xor_b32 s0, s0, s23
	s_sub_i32 s0, s0, s23
	s_mul_i32 s21, s0, s21
	s_sub_i32 s1, s1, s21
	s_add_i32 s44, s1, s20
	s_ashr_i32 s45, s44, 31
	s_lshl_b64 s[20:21], s[44:45], 19
	v_readlane_b32 s22, v252, 10
	v_readlane_b32 s23, v252, 11
	s_add_u32 s46, s22, s20
	s_addc_u32 s47, s23, s21
	s_ashr_i32 s1, s0, 31
	s_lshl_b64 s[20:21], s[0:1], 19
	v_readlane_b32 s22, v252, 18
	v_readlane_b32 s23, v252, 19
	s_add_u32 s48, s22, s20
	s_addc_u32 s49, s23, s21
.LBB0_79:
	s_add_u32 s52, s52, 0x40080
	s_addc_u32 s53, s53, 0
	s_add_u32 s1, s54, 0x100
	s_addc_u32 s20, s55, 0
	s_mov_b32 s21, -2
	s_add_u32 s22, s52, 0xfffc0080
	s_addc_u32 s23, s53, -1
	s_add_i32 s24, 0, 0x10000
	s_add_i32 m0, s62, 0xc000
	s_cmp_eq_u32 s21, 12
	s_cselect_b32 s57, s47, s23
	s_cselect_b32 s56, s46, s22
	s_cselect_b32 s55, s49, s20
	s_cselect_b32 s54, s48, s1
	global_load_lds_dwordx4 v206, s[52:53]
	s_add_i32 m0, s62, 0xe000
	s_nop 0
	global_load_lds_dwordx4 v208, s[52:53]
	s_waitcnt lgkmcnt(8)
	s_barrier
	s_waitcnt lgkmcnt(0)
	v_mfma_f32_16x16x32_bf16 v[160:163], v[52:55], v[92:95], 0
	v_mfma_f32_16x16x32_bf16 v[152:155], v[60:63], v[92:95], 0
	v_mfma_f32_16x16x32_bf16 v[144:147], v[52:55], v[100:103], 0
	v_mfma_f32_16x16x32_bf16 v[140:143], v[60:63], v[100:103], 0
	v_mfma_f32_16x16x32_bf16 v[116:119], v[52:55], v[76:79], 0
	v_mfma_f32_16x16x32_bf16 v[120:123], v[60:63], v[76:79], 0
	v_mfma_f32_16x16x32_bf16 v[124:127], v[52:55], v[84:87], 0
	v_mfma_f32_16x16x32_bf16 v[128:131], v[60:63], v[84:87], 0
	v_mfma_f32_16x16x32_bf16 v[160:163], v[56:59], v[96:99], v[160:163]
	v_mfma_f32_16x16x32_bf16 v[152:155], v[64:67], v[96:99], v[152:155]
	v_mfma_f32_16x16x32_bf16 v[144:147], v[56:59], v[104:107], v[144:147]
	v_mfma_f32_16x16x32_bf16 v[140:143], v[64:67], v[104:107], v[140:143]
	v_mfma_f32_16x16x32_bf16 v[116:119], v[56:59], v[80:83], v[116:119]
	v_mfma_f32_16x16x32_bf16 v[120:123], v[64:67], v[80:83], v[120:123]
	v_mfma_f32_16x16x32_bf16 v[124:127], v[56:59], v[88:91], v[124:127]
	v_mfma_f32_16x16x32_bf16 v[128:131], v[64:67], v[88:91], v[128:131]
	s_barrier
	s_add_i32 s25, 0, 0x14000
	s_add_i32 s22, s24, s60
	s_mov_b32 m0, s22
	ds_read_b128 v[168:171], v198 offset:16384
	ds_read_b128 v[176:179], v198 offset:17408
	ds_read_b128 v[184:187], v198 offset:18432
	global_load_lds_dwordx4 v2, s[54:55]
	s_add_i32 m0, s22, 0x2000
	ds_read_b128 v[192:195], v198 offset:19456
	global_load_lds_dwordx4 v0, s[54:55]
	s_barrier
	s_waitcnt lgkmcnt(0)
	v_mfma_f32_16x16x32_bf16 v[188:191], v[168:171], v[76:79], 0
	v_mfma_f32_16x16x32_bf16 v[76:79], v[184:187], v[76:79], 0
	v_mfma_f32_16x16x32_bf16 v[188:191], v[176:179], v[80:83], v[188:191]
	v_mfma_f32_16x16x32_bf16 v[76:79], v[192:195], v[80:83], v[76:79]
	v_mfma_f32_16x16x32_bf16 v[80:83], v[168:171], v[84:87], 0
	v_mfma_f32_16x16x32_bf16 v[84:87], v[184:187], v[84:87], 0
	v_mfma_f32_16x16x32_bf16 v[80:83], v[176:179], v[88:91], v[80:83]
	v_mfma_f32_16x16x32_bf16 v[84:87], v[192:195], v[88:91], v[84:87]
	v_mfma_f32_16x16x32_bf16 v[88:91], v[168:171], v[92:95], 0
	v_mfma_f32_16x16x32_bf16 v[92:95], v[184:187], v[92:95], 0
	v_mfma_f32_16x16x32_bf16 v[88:91], v[176:179], v[96:99], v[88:91]
	v_mfma_f32_16x16x32_bf16 v[92:95], v[192:195], v[96:99], v[92:95]
	v_mfma_f32_16x16x32_bf16 v[96:99], v[168:171], v[100:103], 0
	v_mfma_f32_16x16x32_bf16 v[100:103], v[184:187], v[100:103], 0
	v_mfma_f32_16x16x32_bf16 v[96:99], v[176:179], v[104:107], v[96:99]
	v_mfma_f32_16x16x32_bf16 v[100:103], v[192:195], v[104:107], v[100:103]
	s_mov_b32 m0, s62
	s_barrier
	ds_read_b128 v[104:107], v239 offset:16384
	ds_read_b128 v[132:135], v239 offset:17408
	ds_read_b128 v[136:139], v239 offset:18432
	ds_read_b128 v[148:151], v239 offset:19456
	ds_read_b128 v[156:159], v239 offset:20480
	ds_read_b128 v[164:167], v239 offset:21504
	ds_read_b128 v[172:175], v239 offset:22528
	global_load_lds_dwordx4 v204, s[56:57]
	s_mov_b32 m0, s63
	ds_read_b128 v[180:183], v239 offset:23552
	global_load_lds_dwordx4 v202, s[56:57]
	s_barrier
	s_waitcnt lgkmcnt(0)
	v_mfma_f32_16x16x32_bf16 v[112:115], v[52:55], v[104:107], 0
	v_mfma_f32_16x16x32_bf16 v[72:75], v[60:63], v[104:107], 0
	v_mfma_f32_16x16x32_bf16 v[48:51], v[52:55], v[136:139], 0
	v_mfma_f32_16x16x32_bf16 v[40:43], v[60:63], v[136:139], 0
	v_mfma_f32_16x16x32_bf16 v[32:35], v[52:55], v[156:159], 0
	v_mfma_f32_16x16x32_bf16 v[24:27], v[60:63], v[156:159], 0
	v_mfma_f32_16x16x32_bf16 v[16:19], v[52:55], v[172:175], 0
	v_mfma_f32_16x16x32_bf16 v[12:15], v[60:63], v[172:175], 0
	v_mfma_f32_16x16x32_bf16 v[112:115], v[56:59], v[132:135], v[112:115]
	v_mfma_f32_16x16x32_bf16 v[72:75], v[64:67], v[132:135], v[72:75]
	v_mfma_f32_16x16x32_bf16 v[48:51], v[56:59], v[148:151], v[48:51]
	v_mfma_f32_16x16x32_bf16 v[40:43], v[64:67], v[148:151], v[40:43]
	v_mfma_f32_16x16x32_bf16 v[32:35], v[56:59], v[164:167], v[32:35]
	v_mfma_f32_16x16x32_bf16 v[24:27], v[64:67], v[164:167], v[24:27]
	v_mfma_f32_16x16x32_bf16 v[16:19], v[56:59], v[180:183], v[16:19]
	v_mfma_f32_16x16x32_bf16 v[12:15], v[64:67], v[180:183], v[12:15]
	s_barrier
	s_add_i32 s24, s25, s60
	s_mov_b32 m0, s24
	s_add_u32 s22, s54, 0x40000
	s_addc_u32 s23, s55, 0
	global_load_lds_dwordx4 v2, s[22:23]
	s_add_i32 m0, s24, 0x2000
	s_waitcnt vmcnt(5)
	global_load_lds_dwordx4 v0, s[22:23]
	s_barrier
	v_mfma_f32_16x16x32_bf16 v[44:47], v[168:171], v[136:139], 0
	v_mfma_f32_16x16x32_bf16 v[36:39], v[184:187], v[136:139], 0
	v_mfma_f32_16x16x32_bf16 v[28:31], v[168:171], v[156:159], 0
	v_mfma_f32_16x16x32_bf16 v[20:23], v[184:187], v[156:159], 0
	v_mfma_f32_16x16x32_bf16 v[8:11], v[168:171], v[172:175], 0
	v_mfma_f32_16x16x32_bf16 v[4:7], v[184:187], v[172:175], 0
	v_mfma_f32_16x16x32_bf16 v[52:55], v[168:171], v[104:107], 0
	v_mfma_f32_16x16x32_bf16 v[56:59], v[184:187], v[104:107], 0
	v_mfma_f32_16x16x32_bf16 v[44:47], v[176:179], v[148:151], v[44:47]
	v_mfma_f32_16x16x32_bf16 v[36:39], v[192:195], v[148:151], v[36:39]
	v_mfma_f32_16x16x32_bf16 v[28:31], v[176:179], v[164:167], v[28:31]
	v_mfma_f32_16x16x32_bf16 v[20:23], v[192:195], v[164:167], v[20:23]
	v_mfma_f32_16x16x32_bf16 v[8:11], v[176:179], v[180:183], v[8:11]
	v_mfma_f32_16x16x32_bf16 v[4:7], v[192:195], v[180:183], v[4:7]
	v_mfma_f32_16x16x32_bf16 v[52:55], v[176:179], v[132:135], v[52:55]
	v_mfma_f32_16x16x32_bf16 v[56:59], v[192:195], v[132:135], v[56:59]
	s_add_i32 s24, 0, 0x18000
	s_barrier
	ds_read_b128 v[60:63], v198 offset:32768
	ds_read_b128 v[64:67], v198 offset:33792
	ds_read_b128 v[68:71], v198 offset:34816
	ds_read_b128 v[104:107], v198 offset:35840
	s_add_u32 s22, s56, 0x40000
	s_addc_u32 s23, s57, 0
	s_mov_b32 m0, s64
	ds_read_b128 v[108:111], v239 offset:32768
	ds_read_b128 v[132:135], v239 offset:33792
	ds_read_b128 v[136:139], v239 offset:34816
	ds_read_b128 v[148:151], v239 offset:35840
	ds_read_b128 v[210:213], v239 offset:36864
	ds_read_b128 v[214:217], v239 offset:37888
	ds_read_b128 v[240:243], v239 offset:38912
	global_load_lds_dwordx4 v204, s[22:23]
	s_mov_b32 m0, s65
	ds_read_b128 v[244:247], v239 offset:39936
	global_load_lds_dwordx4 v202, s[22:23]
	s_waitcnt lgkmcnt(8)
	s_barrier
	s_waitcnt lgkmcnt(0)
	v_mfma_f32_16x16x32_bf16 v[116:119], v[60:63], v[108:111], v[116:119]
	v_mfma_f32_16x16x32_bf16 v[192:195], v[64:67], v[132:135], v[116:119]
	v_mfma_f32_16x16x32_bf16 v[116:119], v[68:71], v[108:111], v[120:123]
	v_mfma_f32_16x16x32_bf16 v[184:187], v[104:107], v[132:135], v[116:119]
	v_mfma_f32_16x16x32_bf16 v[116:119], v[60:63], v[136:139], v[124:127]
	v_mfma_f32_16x16x32_bf16 v[176:179], v[64:67], v[148:151], v[116:119]
	v_mfma_f32_16x16x32_bf16 v[116:119], v[68:71], v[136:139], v[128:131]
	v_mfma_f32_16x16x32_bf16 v[168:171], v[104:107], v[148:151], v[116:119]
	v_mfma_f32_16x16x32_bf16 v[116:119], v[60:63], v[210:213], v[160:163]
	v_mfma_f32_16x16x32_bf16 v[160:163], v[64:67], v[214:217], v[116:119]
	v_mfma_f32_16x16x32_bf16 v[116:119], v[68:71], v[210:213], v[152:155]
	v_mfma_f32_16x16x32_bf16 v[152:155], v[104:107], v[214:217], v[116:119]
	v_mfma_f32_16x16x32_bf16 v[116:119], v[60:63], v[240:243], v[144:147]
	v_mfma_f32_16x16x32_bf16 v[144:147], v[64:67], v[244:247], v[116:119]
	v_mfma_f32_16x16x32_bf16 v[116:119], v[68:71], v[240:243], v[140:143]
	v_mfma_f32_16x16x32_bf16 v[140:143], v[104:107], v[244:247], v[116:119]
	s_barrier
	s_add_i32 s25, 0, 0x1c000
	s_add_i32 s22, s24, s60
	s_mov_b32 m0, s22
	ds_read_b128 v[116:119], v198 offset:49152
	ds_read_b128 v[120:123], v198 offset:50176
	ds_read_b128 v[124:127], v198 offset:51200
	s_add_u32 s98, s54, 0x80
	s_addc_u32 s99, s55, 0
	global_load_lds_dwordx4 v2, s[98:99]
	s_add_i32 m0, s22, 0x2000
	ds_read_b128 v[128:131], v198 offset:52224
	global_load_lds_dwordx4 v0, s[98:99]
	s_barrier
	s_waitcnt lgkmcnt(0)
	v_mfma_f32_16x16x32_bf16 v[76:79], v[124:127], v[108:111], v[76:79]
	v_mfma_f32_16x16x32_bf16 v[180:183], v[128:131], v[132:135], v[76:79]
	v_mfma_f32_16x16x32_bf16 v[76:79], v[116:119], v[136:139], v[80:83]
	v_mfma_f32_16x16x32_bf16 v[172:175], v[120:123], v[148:151], v[76:79]
	v_mfma_f32_16x16x32_bf16 v[76:79], v[124:127], v[136:139], v[84:87]
	v_mfma_f32_16x16x32_bf16 v[156:159], v[116:119], v[108:111], v[188:191]
	v_mfma_f32_16x16x32_bf16 v[164:167], v[128:131], v[148:151], v[76:79]
	v_mfma_f32_16x16x32_bf16 v[76:79], v[116:119], v[210:213], v[88:91]
	v_mfma_f32_16x16x32_bf16 v[188:191], v[120:123], v[132:135], v[156:159]
	v_mfma_f32_16x16x32_bf16 v[156:159], v[120:123], v[214:217], v[76:79]
	v_mfma_f32_16x16x32_bf16 v[76:79], v[124:127], v[210:213], v[92:95]
	v_mfma_f32_16x16x32_bf16 v[148:151], v[128:131], v[214:217], v[76:79]
	v_mfma_f32_16x16x32_bf16 v[76:79], v[116:119], v[240:243], v[96:99]
	v_mfma_f32_16x16x32_bf16 v[136:139], v[120:123], v[244:247], v[76:79]
	v_mfma_f32_16x16x32_bf16 v[76:79], v[124:127], v[240:243], v[100:103]
	v_mfma_f32_16x16x32_bf16 v[132:135], v[128:131], v[244:247], v[76:79]
	s_mov_b32 m0, s72
	s_barrier
	s_nop 2
	ds_read_b128 v[76:79], v239 offset:49152
	ds_read_b128 v[80:83], v239 offset:50176
	ds_read_b128 v[84:87], v239 offset:51200
	ds_read_b128 v[88:91], v239 offset:52224
	ds_read_b128 v[92:95], v239 offset:53248
	ds_read_b128 v[96:99], v239 offset:54272
	ds_read_b128 v[100:103], v239 offset:55296
	s_add_u32 s98, s56, 0x80
	s_addc_u32 s99, s57, 0
	global_load_lds_dwordx4 v204, s[98:99]
	s_mov_b32 m0, s74
	ds_read_b128 v[210:213], v239 offset:56320
	global_load_lds_dwordx4 v202, s[98:99]
	s_barrier
	s_waitcnt lgkmcnt(0)
	v_mfma_f32_16x16x32_bf16 v[108:111], v[60:63], v[76:79], v[112:115]
	v_mfma_f32_16x16x32_bf16 v[72:75], v[68:71], v[76:79], v[72:75]
	v_mfma_f32_16x16x32_bf16 v[48:51], v[60:63], v[84:87], v[48:51]
	v_mfma_f32_16x16x32_bf16 v[40:43], v[68:71], v[84:87], v[40:43]
	v_mfma_f32_16x16x32_bf16 v[32:35], v[60:63], v[92:95], v[32:35]
	v_mfma_f32_16x16x32_bf16 v[24:27], v[68:71], v[92:95], v[24:27]
	v_mfma_f32_16x16x32_bf16 v[16:19], v[60:63], v[100:103], v[16:19]
	v_mfma_f32_16x16x32_bf16 v[12:15], v[68:71], v[100:103], v[12:15]
	v_mfma_f32_16x16x32_bf16 v[112:115], v[64:67], v[80:83], v[108:111]
	v_mfma_f32_16x16x32_bf16 v[72:75], v[104:107], v[80:83], v[72:75]
	v_mfma_f32_16x16x32_bf16 v[48:51], v[64:67], v[88:91], v[48:51]
	v_mfma_f32_16x16x32_bf16 v[40:43], v[104:107], v[88:91], v[40:43]
	v_mfma_f32_16x16x32_bf16 v[32:35], v[64:67], v[96:99], v[32:35]
	v_mfma_f32_16x16x32_bf16 v[24:27], v[104:107], v[96:99], v[24:27]
	v_mfma_f32_16x16x32_bf16 v[16:19], v[64:67], v[210:213], v[16:19]
	v_mfma_f32_16x16x32_bf16 v[12:15], v[104:107], v[210:213], v[12:15]
	s_barrier
	s_add_i32 s24, s25, s60
	s_mov_b32 m0, s24
	s_add_u32 s22, s54, 0x40080
	s_addc_u32 s23, s55, 0
	global_load_lds_dwordx4 v2, s[22:23]
	s_add_i32 m0, s24, 0x2000
	s_waitcnt vmcnt(5)
	global_load_lds_dwordx4 v0, s[22:23]
	s_barrier
	v_mfma_f32_16x16x32_bf16 v[52:55], v[116:119], v[76:79], v[52:55]
	v_mfma_f32_16x16x32_bf16 v[108:111], v[120:123], v[80:83], v[52:55]
	v_mfma_f32_16x16x32_bf16 v[52:55], v[124:127], v[76:79], v[56:59]
	v_mfma_f32_16x16x32_bf16 v[44:47], v[116:119], v[84:87], v[44:47]
	v_mfma_f32_16x16x32_bf16 v[36:39], v[124:127], v[84:87], v[36:39]
	v_mfma_f32_16x16x32_bf16 v[28:31], v[116:119], v[92:95], v[28:31]
	v_mfma_f32_16x16x32_bf16 v[20:23], v[124:127], v[92:95], v[20:23]
	v_mfma_f32_16x16x32_bf16 v[8:11], v[116:119], v[100:103], v[8:11]
	v_mfma_f32_16x16x32_bf16 v[4:7], v[124:127], v[100:103], v[4:7]
	v_mfma_f32_16x16x32_bf16 v[68:71], v[128:131], v[80:83], v[52:55]
	v_mfma_f32_16x16x32_bf16 v[44:47], v[120:123], v[88:91], v[44:47]
	v_mfma_f32_16x16x32_bf16 v[36:39], v[128:131], v[88:91], v[36:39]
	v_mfma_f32_16x16x32_bf16 v[28:31], v[120:123], v[96:99], v[28:31]
	v_mfma_f32_16x16x32_bf16 v[20:23], v[128:131], v[96:99], v[20:23]
	v_mfma_f32_16x16x32_bf16 v[8:11], v[120:123], v[210:213], v[8:11]
	v_mfma_f32_16x16x32_bf16 v[4:7], v[128:131], v[210:213], v[4:7]
	s_add_i32 s21, s21, 2
	s_add_u32 s52, s52, 0x100
	s_addc_u32 s53, s53, 0
	s_add_u32 s1, s1, 0x100
	s_addc_u32 s20, s20, 0
	s_cmp_gt_u32 s21, 13
	s_barrier
	s_cbranch_scc1 .Lpeel_out_80

.LBB0_129:
	v_add_u32_e32 v194, 0x10000, v143
	ds_read_b128 v[146:149], v194
	ds_read_b128 v[150:153], v194 offset:1024
	ds_read_b128 v[154:157], v194 offset:2048
	ds_read_b128 v[158:161], v194 offset:3072
	ds_read_b128 v[162:165], v144
	ds_read_b128 v[166:169], v144 offset:1024
	ds_read_b128 v[170:173], v144 offset:2048
	ds_read_b128 v[174:177], v144 offset:3072
	ds_read_b128 v[178:181], v144 offset:4096
	ds_read_b128 v[182:185], v144 offset:5120
	ds_read_b128 v[186:189], v144 offset:6144
	ds_read_b128 v[190:193], v144 offset:7168
	s_add_i32 s61, s61, 1
	s_mul_i32 s20, s61, s62
	s_mul_hi_u32 s21, s61, s58
	s_add_i32 s21, s21, s20
	s_mul_i32 s20, s61, s58
	s_add_u32 s52, s20, s30
	s_addc_u32 s53, s21, s36
	v_mov_b64_e32 v[4:5], 0x1ff
	v_cmp_gt_i64_e64 s[38:39], s[52:53], v[4:5]
	s_and_b64 vcc, exec, s[38:39]
	s_cbranch_vccnz .LBB0_135
	s_ashr_i32 s20, s52, 31
	s_lshr_b32 s20, s20, 29
	s_add_i32 s20, s52, s20
	s_and_b32 s21, s20, -8
	s_sub_i32 s21, s52, s21
	s_cmp_gt_i32 s21, -1
	s_mov_b64 s[40:41], -1
	s_cbranch_scc0 .LBB0_132
	s_lshl_b32 s22, s21, 6
	s_mov_b64 s[40:41], 0

.LBB0_135:
	s_add_u32 s48, s48, 0x40080
	s_addc_u32 s49, s49, 0
	s_add_u32 s20, s50, 0x100
	s_addc_u32 s21, s51, 0
	s_mov_b32 s22, -2
	s_add_u32 s23, s48, 0xfffc0080
	s_addc_u32 s24, s49, -1
	s_add_i32 s25, 0, 0x10000
	s_add_i32 m0, s54, 0xc000
	s_cmp_eq_u32 s22, 12
	s_cselect_b32 s53, s45, s24
	s_cselect_b32 s52, s44, s23
	s_cselect_b32 s51, s47, s21
	s_cselect_b32 s50, s46, s20
	global_load_lds_dwordx4 v138, s[48:49]
	s_add_i32 m0, s54, 0xe000
	s_nop 0
	global_load_lds_dwordx4 v140, s[48:49]
	s_waitcnt lgkmcnt(8)
	s_barrier
	s_waitcnt lgkmcnt(0)
	v_mfma_f32_16x16x32_bf16 v[128:131], v[146:149], v[162:165], 0
	v_mfma_f32_16x16x32_bf16 v[124:127], v[154:157], v[162:165], 0
	v_mfma_f32_16x16x32_bf16 v[120:123], v[146:149], v[170:173], 0
	v_mfma_f32_16x16x32_bf16 v[116:119], v[154:157], v[170:173], 0
	v_mfma_f32_16x16x32_bf16 v[104:107], v[146:149], v[178:181], 0
	v_mfma_f32_16x16x32_bf16 v[100:103], v[154:157], v[178:181], 0
	v_mfma_f32_16x16x32_bf16 v[88:91], v[146:149], v[186:189], 0
	v_mfma_f32_16x16x32_bf16 v[84:87], v[154:157], v[186:189], 0
	v_mfma_f32_16x16x32_bf16 v[128:131], v[150:153], v[166:169], v[128:131]
	v_mfma_f32_16x16x32_bf16 v[124:127], v[158:161], v[166:169], v[124:127]
	v_mfma_f32_16x16x32_bf16 v[120:123], v[150:153], v[174:177], v[120:123]
	v_mfma_f32_16x16x32_bf16 v[116:119], v[158:161], v[174:177], v[116:119]
	v_mfma_f32_16x16x32_bf16 v[104:107], v[150:153], v[182:185], v[104:107]
	v_mfma_f32_16x16x32_bf16 v[100:103], v[158:161], v[182:185], v[100:103]
	v_mfma_f32_16x16x32_bf16 v[88:91], v[150:153], v[190:193], v[88:91]
	v_mfma_f32_16x16x32_bf16 v[84:87], v[158:161], v[190:193], v[84:87]
	s_barrier
	s_add_i32 s23, 0, 0x14000
	s_add_i32 s24, s25, s37
	s_mov_b32 m0, s24
	ds_read_b128 v[202:205], v194 offset:16384
	ds_read_b128 v[206:209], v194 offset:17408
	ds_read_b128 v[210:213], v194 offset:18432
	global_load_lds_dwordx4 v132, s[50:51]
	s_add_i32 m0, s24, 0x2000
	ds_read_b128 v[214:217], v194 offset:19456
	global_load_lds_dwordx4 v136, s[50:51]
	s_barrier
	s_waitcnt lgkmcnt(0)
	v_mfma_f32_16x16x32_bf16 v[112:115], v[202:205], v[162:165], 0
	v_mfma_f32_16x16x32_bf16 v[108:111], v[210:213], v[162:165], 0
	v_mfma_f32_16x16x32_bf16 v[96:99], v[202:205], v[170:173], 0
	v_mfma_f32_16x16x32_bf16 v[92:95], v[210:213], v[170:173], 0
	v_mfma_f32_16x16x32_bf16 v[80:83], v[202:205], v[178:181], 0
	v_mfma_f32_16x16x32_bf16 v[76:79], v[210:213], v[178:181], 0
	v_mfma_f32_16x16x32_bf16 v[72:75], v[202:205], v[186:189], 0
	v_mfma_f32_16x16x32_bf16 v[68:71], v[210:213], v[186:189], 0
	v_mfma_f32_16x16x32_bf16 v[112:115], v[206:209], v[166:169], v[112:115]
	v_mfma_f32_16x16x32_bf16 v[108:111], v[214:217], v[166:169], v[108:111]
	v_mfma_f32_16x16x32_bf16 v[96:99], v[206:209], v[174:177], v[96:99]
	v_mfma_f32_16x16x32_bf16 v[92:95], v[214:217], v[174:177], v[92:95]
	v_mfma_f32_16x16x32_bf16 v[80:83], v[206:209], v[182:185], v[80:83]
	v_mfma_f32_16x16x32_bf16 v[76:79], v[214:217], v[182:185], v[76:79]
	v_mfma_f32_16x16x32_bf16 v[72:75], v[206:209], v[190:193], v[72:75]
	v_mfma_f32_16x16x32_bf16 v[68:71], v[214:217], v[190:193], v[68:71]
	s_mov_b32 m0, s54
	s_barrier
	ds_read_b128 v[162:165], v144 offset:16384
	ds_read_b128 v[166:169], v144 offset:17408
	ds_read_b128 v[170:173], v144 offset:18432
	ds_read_b128 v[174:177], v144 offset:19456
	ds_read_b128 v[178:181], v144 offset:20480
	ds_read_b128 v[182:185], v144 offset:21504
	ds_read_b128 v[186:189], v144 offset:22528
	global_load_lds_dwordx4 v0, s[52:53]
	s_mov_b32 m0, s55
	ds_read_b128 v[190:193], v144 offset:23552
	global_load_lds_dwordx4 v134, s[52:53]
	s_barrier
	s_waitcnt lgkmcnt(0)
	v_mfma_f32_16x16x32_bf16 v[64:67], v[146:149], v[162:165], 0
	v_mfma_f32_16x16x32_bf16 v[60:63], v[154:157], v[162:165], 0
	v_mfma_f32_16x16x32_bf16 v[56:59], v[146:149], v[170:173], 0
	v_mfma_f32_16x16x32_bf16 v[52:55], v[154:157], v[170:173], 0
	v_mfma_f32_16x16x32_bf16 v[40:43], v[146:149], v[178:181], 0
	v_mfma_f32_16x16x32_bf16 v[36:39], v[154:157], v[178:181], 0
	v_mfma_f32_16x16x32_bf16 v[24:27], v[146:149], v[186:189], 0
	v_mfma_f32_16x16x32_bf16 v[16:19], v[154:157], v[186:189], 0
	v_mfma_f32_16x16x32_bf16 v[64:67], v[150:153], v[166:169], v[64:67]
	v_mfma_f32_16x16x32_bf16 v[60:63], v[158:161], v[166:169], v[60:63]
	v_mfma_f32_16x16x32_bf16 v[56:59], v[150:153], v[174:177], v[56:59]
	v_mfma_f32_16x16x32_bf16 v[52:55], v[158:161], v[174:177], v[52:55]
	v_mfma_f32_16x16x32_bf16 v[40:43], v[150:153], v[182:185], v[40:43]
	v_mfma_f32_16x16x32_bf16 v[36:39], v[158:161], v[182:185], v[36:39]
	v_mfma_f32_16x16x32_bf16 v[24:27], v[150:153], v[190:193], v[24:27]
	v_mfma_f32_16x16x32_bf16 v[16:19], v[158:161], v[190:193], v[16:19]
	s_barrier
	s_add_i32 s23, s23, s37
	s_mov_b32 m0, s23
	s_add_u32 s24, s50, 0x40000
	s_addc_u32 s25, s51, 0
	global_load_lds_dwordx4 v132, s[24:25]
	s_add_i32 m0, s23, 0x2000
	s_waitcnt vmcnt(5)
	global_load_lds_dwordx4 v136, s[24:25]
	s_barrier
	v_mfma_f32_16x16x32_bf16 v[48:51], v[202:205], v[162:165], 0
	v_mfma_f32_16x16x32_bf16 v[44:47], v[210:213], v[162:165], 0
	v_mfma_f32_16x16x32_bf16 v[32:35], v[202:205], v[170:173], 0
	v_mfma_f32_16x16x32_bf16 v[28:31], v[210:213], v[170:173], 0
	v_mfma_f32_16x16x32_bf16 v[20:23], v[202:205], v[178:181], 0
	v_mfma_f32_16x16x32_bf16 v[12:15], v[210:213], v[178:181], 0
	v_mfma_f32_16x16x32_bf16 v[8:11], v[202:205], v[186:189], 0
	v_mfma_f32_16x16x32_bf16 v[4:7], v[210:213], v[186:189], 0
	v_mfma_f32_16x16x32_bf16 v[48:51], v[206:209], v[166:169], v[48:51]
	v_mfma_f32_16x16x32_bf16 v[44:47], v[214:217], v[166:169], v[44:47]
	v_mfma_f32_16x16x32_bf16 v[32:35], v[206:209], v[174:177], v[32:35]
	v_mfma_f32_16x16x32_bf16 v[28:31], v[214:217], v[174:177], v[28:31]
	v_mfma_f32_16x16x32_bf16 v[20:23], v[206:209], v[182:185], v[20:23]
	v_mfma_f32_16x16x32_bf16 v[12:15], v[214:217], v[182:185], v[12:15]
	v_mfma_f32_16x16x32_bf16 v[8:11], v[206:209], v[190:193], v[8:11]
	v_mfma_f32_16x16x32_bf16 v[4:7], v[214:217], v[190:193], v[4:7]
	s_add_i32 s23, 0, 0x18000
	s_barrier
	ds_read_b128 v[146:149], v194 offset:32768
	ds_read_b128 v[150:153], v194 offset:33792
	ds_read_b128 v[154:157], v194 offset:34816
	ds_read_b128 v[158:161], v194 offset:35840
	s_add_u32 s24, s52, 0x40000
	s_addc_u32 s25, s53, 0
	s_mov_b32 m0, s56
	ds_read_b128 v[162:165], v144 offset:32768
	ds_read_b128 v[166:169], v144 offset:33792
	ds_read_b128 v[170:173], v144 offset:34816
	ds_read_b128 v[174:177], v144 offset:35840
	ds_read_b128 v[178:181], v144 offset:36864
	ds_read_b128 v[182:185], v144 offset:37888
	ds_read_b128 v[186:189], v144 offset:38912
	global_load_lds_dwordx4 v0, s[24:25]
	s_mov_b32 m0, s57
	ds_read_b128 v[190:193], v144 offset:39936
	global_load_lds_dwordx4 v134, s[24:25]
	s_waitcnt lgkmcnt(8)
	s_barrier
	s_waitcnt lgkmcnt(0)
	v_mfma_f32_16x16x32_bf16 v[128:131], v[146:149], v[162:165], v[128:131]
	v_mfma_f32_16x16x32_bf16 v[124:127], v[154:157], v[162:165], v[124:127]
	v_mfma_f32_16x16x32_bf16 v[120:123], v[146:149], v[170:173], v[120:123]
	v_mfma_f32_16x16x32_bf16 v[116:119], v[154:157], v[170:173], v[116:119]
	v_mfma_f32_16x16x32_bf16 v[104:107], v[146:149], v[178:181], v[104:107]
	v_mfma_f32_16x16x32_bf16 v[100:103], v[154:157], v[178:181], v[100:103]
	v_mfma_f32_16x16x32_bf16 v[88:91], v[146:149], v[186:189], v[88:91]
	v_mfma_f32_16x16x32_bf16 v[84:87], v[154:157], v[186:189], v[84:87]
	v_mfma_f32_16x16x32_bf16 v[128:131], v[150:153], v[166:169], v[128:131]
	v_mfma_f32_16x16x32_bf16 v[124:127], v[158:161], v[166:169], v[124:127]
	v_mfma_f32_16x16x32_bf16 v[120:123], v[150:153], v[174:177], v[120:123]
	v_mfma_f32_16x16x32_bf16 v[116:119], v[158:161], v[174:177], v[116:119]
	v_mfma_f32_16x16x32_bf16 v[104:107], v[150:153], v[182:185], v[104:107]
	v_mfma_f32_16x16x32_bf16 v[100:103], v[158:161], v[182:185], v[100:103]
	v_mfma_f32_16x16x32_bf16 v[88:91], v[150:153], v[190:193], v[88:91]
	v_mfma_f32_16x16x32_bf16 v[84:87], v[158:161], v[190:193], v[84:87]
	s_barrier
	s_add_i32 s26, 0, 0x1c000
	s_add_i32 s23, s23, s37
	s_mov_b32 m0, s23
	ds_read_b128 v[202:205], v194 offset:49152
	ds_read_b128 v[206:209], v194 offset:50176
	ds_read_b128 v[210:213], v194 offset:51200
	s_add_u32 s98, s50, 0x80
	s_addc_u32 s99, s51, 0
	global_load_lds_dwordx4 v132, s[98:99]
	s_add_i32 m0, s23, 0x2000
	ds_read_b128 v[214:217], v194 offset:52224
	global_load_lds_dwordx4 v136, s[98:99]
	s_barrier
	s_waitcnt lgkmcnt(0)
	v_mfma_f32_16x16x32_bf16 v[112:115], v[202:205], v[162:165], v[112:115]
	v_mfma_f32_16x16x32_bf16 v[108:111], v[210:213], v[162:165], v[108:111]
	v_mfma_f32_16x16x32_bf16 v[96:99], v[202:205], v[170:173], v[96:99]
	v_mfma_f32_16x16x32_bf16 v[92:95], v[210:213], v[170:173], v[92:95]
	v_mfma_f32_16x16x32_bf16 v[80:83], v[202:205], v[178:181], v[80:83]
	v_mfma_f32_16x16x32_bf16 v[76:79], v[210:213], v[178:181], v[76:79]
	v_mfma_f32_16x16x32_bf16 v[72:75], v[202:205], v[186:189], v[72:75]
	v_mfma_f32_16x16x32_bf16 v[68:71], v[210:213], v[186:189], v[68:71]
	v_mfma_f32_16x16x32_bf16 v[112:115], v[206:209], v[166:169], v[112:115]
	v_mfma_f32_16x16x32_bf16 v[108:111], v[214:217], v[166:169], v[108:111]
	v_mfma_f32_16x16x32_bf16 v[96:99], v[206:209], v[174:177], v[96:99]
	v_mfma_f32_16x16x32_bf16 v[92:95], v[214:217], v[174:177], v[92:95]
	v_mfma_f32_16x16x32_bf16 v[80:83], v[206:209], v[182:185], v[80:83]
	v_mfma_f32_16x16x32_bf16 v[76:79], v[214:217], v[182:185], v[76:79]
	v_mfma_f32_16x16x32_bf16 v[72:75], v[206:209], v[190:193], v[72:75]
	v_mfma_f32_16x16x32_bf16 v[68:71], v[214:217], v[190:193], v[68:71]
	s_mov_b32 m0, s59
	s_barrier
	ds_read_b128 v[162:165], v144 offset:49152
	ds_read_b128 v[166:169], v144 offset:50176
	ds_read_b128 v[170:173], v144 offset:51200
	ds_read_b128 v[174:177], v144 offset:52224
	ds_read_b128 v[178:181], v144 offset:53248
	ds_read_b128 v[182:185], v144 offset:54272
	ds_read_b128 v[186:189], v144 offset:55296
	s_add_u32 s98, s52, 0x80
	s_addc_u32 s99, s53, 0
	global_load_lds_dwordx4 v0, s[98:99]
	s_mov_b32 m0, s60
	ds_read_b128 v[190:193], v144 offset:56320
	global_load_lds_dwordx4 v134, s[98:99]
	s_barrier
	s_waitcnt lgkmcnt(0)
	v_mfma_f32_16x16x32_bf16 v[64:67], v[146:149], v[162:165], v[64:67]
	v_mfma_f32_16x16x32_bf16 v[60:63], v[154:157], v[162:165], v[60:63]
	v_mfma_f32_16x16x32_bf16 v[56:59], v[146:149], v[170:173], v[56:59]
	v_mfma_f32_16x16x32_bf16 v[52:55], v[154:157], v[170:173], v[52:55]
	v_mfma_f32_16x16x32_bf16 v[40:43], v[146:149], v[178:181], v[40:43]
	v_mfma_f32_16x16x32_bf16 v[36:39], v[154:157], v[178:181], v[36:39]
	v_mfma_f32_16x16x32_bf16 v[24:27], v[146:149], v[186:189], v[24:27]
	v_mfma_f32_16x16x32_bf16 v[16:19], v[154:157], v[186:189], v[16:19]
	v_mfma_f32_16x16x32_bf16 v[64:67], v[150:153], v[166:169], v[64:67]
	v_mfma_f32_16x16x32_bf16 v[60:63], v[158:161], v[166:169], v[60:63]
	v_mfma_f32_16x16x32_bf16 v[56:59], v[150:153], v[174:177], v[56:59]
	v_mfma_f32_16x16x32_bf16 v[52:55], v[158:161], v[174:177], v[52:55]
	v_mfma_f32_16x16x32_bf16 v[40:43], v[150:153], v[182:185], v[40:43]
	v_mfma_f32_16x16x32_bf16 v[36:39], v[158:161], v[182:185], v[36:39]
	v_mfma_f32_16x16x32_bf16 v[24:27], v[150:153], v[190:193], v[24:27]
	v_mfma_f32_16x16x32_bf16 v[16:19], v[158:161], v[190:193], v[16:19]
	s_barrier
	s_add_i32 s23, s26, s37
	s_mov_b32 m0, s23
	s_add_u32 s24, s50, 0x40080
	s_addc_u32 s25, s51, 0
	global_load_lds_dwordx4 v132, s[24:25]
	s_add_i32 m0, s23, 0x2000
	s_waitcnt vmcnt(5)
	global_load_lds_dwordx4 v136, s[24:25]
	s_barrier
	v_mfma_f32_16x16x32_bf16 v[48:51], v[202:205], v[162:165], v[48:51]
	v_mfma_f32_16x16x32_bf16 v[44:47], v[210:213], v[162:165], v[44:47]
	v_mfma_f32_16x16x32_bf16 v[32:35], v[202:205], v[170:173], v[32:35]
	v_mfma_f32_16x16x32_bf16 v[28:31], v[210:213], v[170:173], v[28:31]
	v_mfma_f32_16x16x32_bf16 v[20:23], v[202:205], v[178:181], v[20:23]
	v_mfma_f32_16x16x32_bf16 v[12:15], v[210:213], v[178:181], v[12:15]
	v_mfma_f32_16x16x32_bf16 v[8:11], v[202:205], v[186:189], v[8:11]
	v_mfma_f32_16x16x32_bf16 v[4:7], v[210:213], v[186:189], v[4:7]
	v_mfma_f32_16x16x32_bf16 v[48:51], v[206:209], v[166:169], v[48:51]
	v_mfma_f32_16x16x32_bf16 v[44:47], v[214:217], v[166:169], v[44:47]
	v_mfma_f32_16x16x32_bf16 v[32:35], v[206:209], v[174:177], v[32:35]
	v_mfma_f32_16x16x32_bf16 v[28:31], v[214:217], v[174:177], v[28:31]
	v_mfma_f32_16x16x32_bf16 v[20:23], v[206:209], v[182:185], v[20:23]
	v_mfma_f32_16x16x32_bf16 v[12:15], v[214:217], v[182:185], v[12:15]
	v_mfma_f32_16x16x32_bf16 v[8:11], v[206:209], v[190:193], v[8:11]
	v_mfma_f32_16x16x32_bf16 v[4:7], v[214:217], v[190:193], v[4:7]
	s_add_i32 s22, s22, 2
	s_add_u32 s48, s48, 0x100
	s_addc_u32 s49, s49, 0
	s_add_u32 s20, s20, 0x100
	s_addc_u32 s21, s21, 0
	s_cmp_gt_u32 s22, 13
	s_barrier
	s_cbranch_scc1 .Lpeel_out_136

.LBB0_235:
	v_add_u32_e32 v216, 0x10000, v187
	ds_read_b128 v[132:135], v216
	ds_read_b128 v[136:139], v216 offset:1024
	ds_read_b128 v[140:143], v216 offset:2048
	ds_read_b128 v[144:147], v216 offset:3072
	ds_read_b128 v[148:151], v240
	ds_read_b128 v[152:155], v240 offset:1024
	ds_read_b128 v[156:159], v240 offset:2048
	ds_read_b128 v[160:163], v240 offset:3072
	ds_read_b128 v[164:167], v240 offset:4096
	ds_read_b128 v[168:171], v240 offset:5120
	ds_read_b128 v[172:175], v240 offset:6144
	ds_read_b128 v[204:207], v240 offset:7168
	s_add_i32 s51, s51, 1
	s_mul_i32 s20, s51, s70
	s_mul_hi_u32 s21, s51, s83
	s_add_i32 s21, s21, s20
	s_mul_i32 s20, s51, s83
	s_add_u32 s46, s20, s9
	s_addc_u32 s47, s21, s78
	v_mov_b64_e32 v[4:5], 0x3ff
	v_cmp_gt_i64_e64 s[42:43], s[46:47], v[4:5]
	s_and_b64 vcc, exec, s[42:43]
	s_cbranch_vccnz .LBB0_241
	s_ashr_i32 s20, s46, 31
	s_lshr_b32 s20, s20, 29
	s_add_i32 s20, s46, s20
	s_and_b32 s21, s20, -8
	s_sub_i32 s21, s46, s21
	s_cmp_gt_i32 s21, -1
	s_mov_b64 s[46:47], -1
	s_cbranch_scc0 .LBB0_238
	s_lshl_b32 s22, s21, 7
	s_mov_b64 s[46:47], 0

.LBB0_241:
	s_add_u32 s0, s0, 0x40080
	s_addc_u32 s1, s1, 0
	s_add_u32 s20, s44, 0x100
	s_addc_u32 s21, s45, 0
	s_mov_b32 s22, -2
	s_add_u32 s23, s0, 0xfffc0080
	s_addc_u32 s24, s1, -1
	s_add_i32 s25, 0, 0x10000
	s_add_i32 m0, s67, 0xc000
	s_cmp_eq_u32 s22, 12
	s_cselect_b32 s47, s57, s24
	s_cselect_b32 s46, s56, s23
	s_cselect_b32 s45, s59, s21
	s_cselect_b32 s44, s58, s20
	global_load_lds_dwordx4 v194, s[0:1]
	s_add_i32 m0, s67, 0xe000
	s_nop 0
	global_load_lds_dwordx4 v202, s[0:1]
	s_waitcnt lgkmcnt(8)
	s_barrier
	s_waitcnt lgkmcnt(0)
	v_mfma_f32_16x16x32_bf16 v[128:131], v[132:135], v[148:151], 0
	v_mfma_f32_16x16x32_bf16 v[124:127], v[140:143], v[148:151], 0
	v_mfma_f32_16x16x32_bf16 v[120:123], v[132:135], v[156:159], 0
	v_mfma_f32_16x16x32_bf16 v[116:119], v[140:143], v[156:159], 0
	v_mfma_f32_16x16x32_bf16 v[112:115], v[132:135], v[164:167], 0
	v_mfma_f32_16x16x32_bf16 v[108:111], v[140:143], v[164:167], 0
	v_mfma_f32_16x16x32_bf16 v[104:107], v[132:135], v[172:175], 0
	v_mfma_f32_16x16x32_bf16 v[100:103], v[140:143], v[172:175], 0
	v_mfma_f32_16x16x32_bf16 v[128:131], v[136:139], v[152:155], v[128:131]
	v_mfma_f32_16x16x32_bf16 v[124:127], v[144:147], v[152:155], v[124:127]
	v_mfma_f32_16x16x32_bf16 v[120:123], v[136:139], v[160:163], v[120:123]
	v_mfma_f32_16x16x32_bf16 v[116:119], v[144:147], v[160:163], v[116:119]
	v_mfma_f32_16x16x32_bf16 v[112:115], v[136:139], v[168:171], v[112:115]
	v_mfma_f32_16x16x32_bf16 v[108:111], v[144:147], v[168:171], v[108:111]
	v_mfma_f32_16x16x32_bf16 v[104:107], v[136:139], v[204:207], v[104:107]
	v_mfma_f32_16x16x32_bf16 v[100:103], v[144:147], v[204:207], v[100:103]
	s_barrier
	s_add_i32 s23, 0, 0x14000
	s_add_i32 s24, s25, s61
	s_mov_b32 m0, s24
	ds_read_b128 v[208:211], v216 offset:16384
	ds_read_b128 v[212:215], v216 offset:17408
	ds_read_b128 v[242:245], v216 offset:18432
	global_load_lds_dwordx4 v176, s[44:45]
	s_add_i32 m0, s24, 0x2000
	ds_read_b128 v[246:249], v216 offset:19456
	global_load_lds_dwordx4 v180, s[44:45]
	s_barrier
	s_waitcnt lgkmcnt(0)
	v_mfma_f32_16x16x32_bf16 v[64:67], v[208:211], v[148:151], 0
	v_mfma_f32_16x16x32_bf16 v[60:63], v[242:245], v[148:151], 0
	v_mfma_f32_16x16x32_bf16 v[56:59], v[208:211], v[156:159], 0
	v_mfma_f32_16x16x32_bf16 v[52:55], v[242:245], v[156:159], 0
	v_mfma_f32_16x16x32_bf16 v[48:51], v[208:211], v[164:167], 0
	v_mfma_f32_16x16x32_bf16 v[44:47], v[242:245], v[164:167], 0
	v_mfma_f32_16x16x32_bf16 v[40:43], v[208:211], v[172:175], 0
	v_mfma_f32_16x16x32_bf16 v[36:39], v[242:245], v[172:175], 0
	v_mfma_f32_16x16x32_bf16 v[64:67], v[212:215], v[152:155], v[64:67]
	v_mfma_f32_16x16x32_bf16 v[60:63], v[246:249], v[152:155], v[60:63]
	v_mfma_f32_16x16x32_bf16 v[56:59], v[212:215], v[160:163], v[56:59]
	v_mfma_f32_16x16x32_bf16 v[52:55], v[246:249], v[160:163], v[52:55]
	v_mfma_f32_16x16x32_bf16 v[48:51], v[212:215], v[168:171], v[48:51]
	v_mfma_f32_16x16x32_bf16 v[44:47], v[246:249], v[168:171], v[44:47]
	v_mfma_f32_16x16x32_bf16 v[40:43], v[212:215], v[204:207], v[40:43]
	v_mfma_f32_16x16x32_bf16 v[36:39], v[246:249], v[204:207], v[36:39]
	s_mov_b32 m0, s67
	s_barrier
	ds_read_b128 v[148:151], v240 offset:16384
	ds_read_b128 v[152:155], v240 offset:17408
	ds_read_b128 v[156:159], v240 offset:18432
	ds_read_b128 v[160:163], v240 offset:19456
	ds_read_b128 v[164:167], v240 offset:20480
	ds_read_b128 v[168:171], v240 offset:21504
	ds_read_b128 v[172:175], v240 offset:22528
	global_load_lds_dwordx4 v0, s[46:47]
	s_mov_b32 m0, s74
	ds_read_b128 v[204:207], v240 offset:23552
	global_load_lds_dwordx4 v178, s[46:47]
	s_barrier
	s_waitcnt lgkmcnt(0)
	v_mfma_f32_16x16x32_bf16 v[96:99], v[132:135], v[148:151], 0
	v_mfma_f32_16x16x32_bf16 v[92:95], v[140:143], v[148:151], 0
	v_mfma_f32_16x16x32_bf16 v[88:91], v[132:135], v[156:159], 0
	v_mfma_f32_16x16x32_bf16 v[84:87], v[140:143], v[156:159], 0
	v_mfma_f32_16x16x32_bf16 v[80:83], v[132:135], v[164:167], 0
	v_mfma_f32_16x16x32_bf16 v[76:79], v[140:143], v[164:167], 0
	v_mfma_f32_16x16x32_bf16 v[72:75], v[132:135], v[172:175], 0
	v_mfma_f32_16x16x32_bf16 v[68:71], v[140:143], v[172:175], 0
	v_mfma_f32_16x16x32_bf16 v[96:99], v[136:139], v[152:155], v[96:99]
	v_mfma_f32_16x16x32_bf16 v[92:95], v[144:147], v[152:155], v[92:95]
	v_mfma_f32_16x16x32_bf16 v[88:91], v[136:139], v[160:163], v[88:91]
	v_mfma_f32_16x16x32_bf16 v[84:87], v[144:147], v[160:163], v[84:87]
	v_mfma_f32_16x16x32_bf16 v[80:83], v[136:139], v[168:171], v[80:83]
	v_mfma_f32_16x16x32_bf16 v[76:79], v[144:147], v[168:171], v[76:79]
	v_mfma_f32_16x16x32_bf16 v[72:75], v[136:139], v[204:207], v[72:75]
	v_mfma_f32_16x16x32_bf16 v[68:71], v[144:147], v[204:207], v[68:71]
	s_barrier
	s_add_i32 s23, s23, s61
	s_mov_b32 m0, s23
	s_add_u32 s24, s44, 0x40000
	s_addc_u32 s25, s45, 0
	global_load_lds_dwordx4 v176, s[24:25]
	s_add_i32 m0, s23, 0x2000
	s_waitcnt vmcnt(5)
	global_load_lds_dwordx4 v180, s[24:25]
	s_barrier
	v_mfma_f32_16x16x32_bf16 v[32:35], v[208:211], v[148:151], 0
	v_mfma_f32_16x16x32_bf16 v[28:31], v[242:245], v[148:151], 0
	v_mfma_f32_16x16x32_bf16 v[24:27], v[208:211], v[156:159], 0
	v_mfma_f32_16x16x32_bf16 v[20:23], v[242:245], v[156:159], 0
	v_mfma_f32_16x16x32_bf16 v[16:19], v[208:211], v[164:167], 0
	v_mfma_f32_16x16x32_bf16 v[12:15], v[242:245], v[164:167], 0
	v_mfma_f32_16x16x32_bf16 v[8:11], v[208:211], v[172:175], 0
	v_mfma_f32_16x16x32_bf16 v[4:7], v[242:245], v[172:175], 0
	v_mfma_f32_16x16x32_bf16 v[32:35], v[212:215], v[152:155], v[32:35]
	v_mfma_f32_16x16x32_bf16 v[28:31], v[246:249], v[152:155], v[28:31]
	v_mfma_f32_16x16x32_bf16 v[24:27], v[212:215], v[160:163], v[24:27]
	v_mfma_f32_16x16x32_bf16 v[20:23], v[246:249], v[160:163], v[20:23]
	v_mfma_f32_16x16x32_bf16 v[16:19], v[212:215], v[168:171], v[16:19]
	v_mfma_f32_16x16x32_bf16 v[12:15], v[246:249], v[168:171], v[12:15]
	v_mfma_f32_16x16x32_bf16 v[8:11], v[212:215], v[204:207], v[8:11]
	v_mfma_f32_16x16x32_bf16 v[4:7], v[246:249], v[204:207], v[4:7]
	s_add_i32 s23, 0, 0x18000
	s_barrier
	ds_read_b128 v[132:135], v216 offset:32768
	ds_read_b128 v[136:139], v216 offset:33792
	ds_read_b128 v[140:143], v216 offset:34816
	ds_read_b128 v[144:147], v216 offset:35840
	s_add_u32 s24, s46, 0x40000
	s_addc_u32 s25, s47, 0
	s_mov_b32 m0, s75
	ds_read_b128 v[148:151], v240 offset:32768
	ds_read_b128 v[152:155], v240 offset:33792
	ds_read_b128 v[156:159], v240 offset:34816
	ds_read_b128 v[160:163], v240 offset:35840
	ds_read_b128 v[164:167], v240 offset:36864
	ds_read_b128 v[168:171], v240 offset:37888
	ds_read_b128 v[172:175], v240 offset:38912
	global_load_lds_dwordx4 v0, s[24:25]
	s_mov_b32 m0, s82
	ds_read_b128 v[204:207], v240 offset:39936
	global_load_lds_dwordx4 v178, s[24:25]
	s_waitcnt lgkmcnt(8)
	s_barrier
	s_waitcnt lgkmcnt(0)
	v_mfma_f32_16x16x32_bf16 v[128:131], v[132:135], v[148:151], v[128:131]
	v_mfma_f32_16x16x32_bf16 v[124:127], v[140:143], v[148:151], v[124:127]
	v_mfma_f32_16x16x32_bf16 v[120:123], v[132:135], v[156:159], v[120:123]
	v_mfma_f32_16x16x32_bf16 v[116:119], v[140:143], v[156:159], v[116:119]
	v_mfma_f32_16x16x32_bf16 v[112:115], v[132:135], v[164:167], v[112:115]
	v_mfma_f32_16x16x32_bf16 v[108:111], v[140:143], v[164:167], v[108:111]
	v_mfma_f32_16x16x32_bf16 v[104:107], v[132:135], v[172:175], v[104:107]
	v_mfma_f32_16x16x32_bf16 v[100:103], v[140:143], v[172:175], v[100:103]
	v_mfma_f32_16x16x32_bf16 v[128:131], v[136:139], v[152:155], v[128:131]
	v_mfma_f32_16x16x32_bf16 v[124:127], v[144:147], v[152:155], v[124:127]
	v_mfma_f32_16x16x32_bf16 v[120:123], v[136:139], v[160:163], v[120:123]
	v_mfma_f32_16x16x32_bf16 v[116:119], v[144:147], v[160:163], v[116:119]
	v_mfma_f32_16x16x32_bf16 v[112:115], v[136:139], v[168:171], v[112:115]
	v_mfma_f32_16x16x32_bf16 v[108:111], v[144:147], v[168:171], v[108:111]
	v_mfma_f32_16x16x32_bf16 v[104:107], v[136:139], v[204:207], v[104:107]
	v_mfma_f32_16x16x32_bf16 v[100:103], v[144:147], v[204:207], v[100:103]
	s_barrier
	s_add_i32 s26, 0, 0x1c000
	s_add_i32 s23, s23, s61
	s_mov_b32 m0, s23
	ds_read_b128 v[208:211], v216 offset:49152
	ds_read_b128 v[212:215], v216 offset:50176
	ds_read_b128 v[242:245], v216 offset:51200
	s_add_u32 s98, s44, 0x80
	s_addc_u32 s99, s45, 0
	global_load_lds_dwordx4 v176, s[98:99]
	s_add_i32 m0, s23, 0x2000
	ds_read_b128 v[246:249], v216 offset:52224
	global_load_lds_dwordx4 v180, s[98:99]
	s_barrier
	s_waitcnt lgkmcnt(0)
	v_mfma_f32_16x16x32_bf16 v[64:67], v[208:211], v[148:151], v[64:67]
	v_mfma_f32_16x16x32_bf16 v[60:63], v[242:245], v[148:151], v[60:63]
	v_mfma_f32_16x16x32_bf16 v[56:59], v[208:211], v[156:159], v[56:59]
	v_mfma_f32_16x16x32_bf16 v[52:55], v[242:245], v[156:159], v[52:55]
	v_mfma_f32_16x16x32_bf16 v[48:51], v[208:211], v[164:167], v[48:51]
	v_mfma_f32_16x16x32_bf16 v[44:47], v[242:245], v[164:167], v[44:47]
	v_mfma_f32_16x16x32_bf16 v[40:43], v[208:211], v[172:175], v[40:43]
	v_mfma_f32_16x16x32_bf16 v[36:39], v[242:245], v[172:175], v[36:39]
	v_mfma_f32_16x16x32_bf16 v[64:67], v[212:215], v[152:155], v[64:67]
	v_mfma_f32_16x16x32_bf16 v[60:63], v[246:249], v[152:155], v[60:63]
	v_mfma_f32_16x16x32_bf16 v[56:59], v[212:215], v[160:163], v[56:59]
	v_mfma_f32_16x16x32_bf16 v[52:55], v[246:249], v[160:163], v[52:55]
	v_mfma_f32_16x16x32_bf16 v[48:51], v[212:215], v[168:171], v[48:51]
	v_mfma_f32_16x16x32_bf16 v[44:47], v[246:249], v[168:171], v[44:47]
	v_mfma_f32_16x16x32_bf16 v[40:43], v[212:215], v[204:207], v[40:43]
	v_mfma_f32_16x16x32_bf16 v[36:39], v[246:249], v[204:207], v[36:39]
	s_mov_b32 m0, s48
	s_barrier
	ds_read_b128 v[148:151], v240 offset:49152
	ds_read_b128 v[152:155], v240 offset:50176
	ds_read_b128 v[156:159], v240 offset:51200
	ds_read_b128 v[160:163], v240 offset:52224
	ds_read_b128 v[164:167], v240 offset:53248
	ds_read_b128 v[168:171], v240 offset:54272
	ds_read_b128 v[172:175], v240 offset:55296
	s_add_u32 s98, s46, 0x80
	s_addc_u32 s99, s47, 0
	global_load_lds_dwordx4 v0, s[98:99]
	s_mov_b32 m0, s50
	ds_read_b128 v[204:207], v240 offset:56320
	global_load_lds_dwordx4 v178, s[98:99]
	s_barrier
	s_waitcnt lgkmcnt(0)
	v_mfma_f32_16x16x32_bf16 v[96:99], v[132:135], v[148:151], v[96:99]
	v_mfma_f32_16x16x32_bf16 v[92:95], v[140:143], v[148:151], v[92:95]
	v_mfma_f32_16x16x32_bf16 v[88:91], v[132:135], v[156:159], v[88:91]
	v_mfma_f32_16x16x32_bf16 v[84:87], v[140:143], v[156:159], v[84:87]
	v_mfma_f32_16x16x32_bf16 v[80:83], v[132:135], v[164:167], v[80:83]
	v_mfma_f32_16x16x32_bf16 v[76:79], v[140:143], v[164:167], v[76:79]
	v_mfma_f32_16x16x32_bf16 v[72:75], v[132:135], v[172:175], v[72:75]
	v_mfma_f32_16x16x32_bf16 v[68:71], v[140:143], v[172:175], v[68:71]
	v_mfma_f32_16x16x32_bf16 v[96:99], v[136:139], v[152:155], v[96:99]
	v_mfma_f32_16x16x32_bf16 v[92:95], v[144:147], v[152:155], v[92:95]
	v_mfma_f32_16x16x32_bf16 v[88:91], v[136:139], v[160:163], v[88:91]
	v_mfma_f32_16x16x32_bf16 v[84:87], v[144:147], v[160:163], v[84:87]
	v_mfma_f32_16x16x32_bf16 v[80:83], v[136:139], v[168:171], v[80:83]
	v_mfma_f32_16x16x32_bf16 v[76:79], v[144:147], v[168:171], v[76:79]
	v_mfma_f32_16x16x32_bf16 v[72:75], v[136:139], v[204:207], v[72:75]
	v_mfma_f32_16x16x32_bf16 v[68:71], v[144:147], v[204:207], v[68:71]
	s_barrier
	s_add_i32 s23, s26, s61
	s_mov_b32 m0, s23
	s_add_u32 s24, s44, 0x40080
	s_addc_u32 s25, s45, 0
	global_load_lds_dwordx4 v176, s[24:25]
	s_add_i32 m0, s23, 0x2000
	s_waitcnt vmcnt(5)
	global_load_lds_dwordx4 v180, s[24:25]
	s_barrier
	v_mfma_f32_16x16x32_bf16 v[32:35], v[208:211], v[148:151], v[32:35]
	v_mfma_f32_16x16x32_bf16 v[28:31], v[242:245], v[148:151], v[28:31]
	v_mfma_f32_16x16x32_bf16 v[24:27], v[208:211], v[156:159], v[24:27]
	v_mfma_f32_16x16x32_bf16 v[20:23], v[242:245], v[156:159], v[20:23]
	v_mfma_f32_16x16x32_bf16 v[16:19], v[208:211], v[164:167], v[16:19]
	v_mfma_f32_16x16x32_bf16 v[12:15], v[242:245], v[164:167], v[12:15]
	v_mfma_f32_16x16x32_bf16 v[8:11], v[208:211], v[172:175], v[8:11]
	v_mfma_f32_16x16x32_bf16 v[4:7], v[242:245], v[172:175], v[4:7]
	v_mfma_f32_16x16x32_bf16 v[32:35], v[212:215], v[152:155], v[32:35]
	v_mfma_f32_16x16x32_bf16 v[28:31], v[246:249], v[152:155], v[28:31]
	v_mfma_f32_16x16x32_bf16 v[24:27], v[212:215], v[160:163], v[24:27]
	v_mfma_f32_16x16x32_bf16 v[20:23], v[246:249], v[160:163], v[20:23]
	v_mfma_f32_16x16x32_bf16 v[16:19], v[212:215], v[168:171], v[16:19]
	v_mfma_f32_16x16x32_bf16 v[12:15], v[246:249], v[168:171], v[12:15]
	v_mfma_f32_16x16x32_bf16 v[8:11], v[212:215], v[204:207], v[8:11]
	v_mfma_f32_16x16x32_bf16 v[4:7], v[246:249], v[204:207], v[4:7]
	s_add_i32 s22, s22, 2
	s_add_u32 s0, s0, 0x100
	s_addc_u32 s1, s1, 0
	s_add_u32 s20, s20, 0x100
	s_addc_u32 s21, s21, 0
	s_cmp_gt_u32 s22, 13
	s_barrier
	s_cbranch_scc1 .Lpeel_out_242

.LBB0_420:
	v_add_u32_e32 v216, 0x10000, v187
	ds_read_b128 v[132:135], v216
	ds_read_b128 v[136:139], v216 offset:1024
	ds_read_b128 v[140:143], v216 offset:2048
	ds_read_b128 v[144:147], v216 offset:3072
	ds_read_b128 v[148:151], v240
	ds_read_b128 v[152:155], v240 offset:1024
	ds_read_b128 v[156:159], v240 offset:2048
	ds_read_b128 v[160:163], v240 offset:3072
	ds_read_b128 v[164:167], v240 offset:4096
	ds_read_b128 v[168:171], v240 offset:5120
	ds_read_b128 v[172:175], v240 offset:6144
	ds_read_b128 v[204:207], v240 offset:7168
	s_add_i32 s51, s51, 1
	s_mul_i32 s20, s51, s31
	s_mul_hi_u32 s21, s51, s10
	s_add_i32 s21, s21, s20
	s_mul_i32 s20, s51, s10
	s_add_u32 s46, s20, s66
	s_addc_u32 s47, s21, s78
	v_mov_b64_e32 v[4:5], 0xd9a
	v_cmp_gt_i64_e64 s[42:43], s[46:47], v[4:5]
	s_and_b64 vcc, exec, s[42:43]
	s_cbranch_vccnz .LBB0_426
	s_ashr_i32 s20, s46, 31
	s_lshr_b32 s20, s20, 29
	s_add_i32 s20, s46, s20
	s_and_b32 s21, s20, -8
	s_sub_i32 s21, s46, s21
	s_cmp_gt_i32 s21, 2
	s_mov_b64 s[46:47], -1
	s_cbranch_scc0 .LBB0_423
	s_mul_i32 s22, s21, 0x1b3
	s_add_i32 s22, s22, 3
	s_mov_b64 s[46:47], 0

.LBB0_426:
	s_add_u32 s0, s0, 0x40080
	s_addc_u32 s1, s1, 0
	s_add_u32 s20, s44, 0x100
	s_addc_u32 s21, s45, 0
	s_mov_b32 s22, -2
	s_add_u32 s23, s0, 0xfffc0080
	s_addc_u32 s24, s1, -1
	s_add_i32 s25, 0, 0x10000
	s_add_i32 m0, s74, 0xc000
	s_cmp_eq_u32 s22, 12
	s_cselect_b32 s47, s57, s24
	s_cselect_b32 s46, s56, s23
	s_cselect_b32 s45, s59, s21
	s_cselect_b32 s44, s58, s20
	global_load_lds_dwordx4 v194, s[0:1]
	s_add_i32 m0, s74, 0xe000
	s_nop 0
	global_load_lds_dwordx4 v202, s[0:1]
	s_waitcnt lgkmcnt(8)
	s_barrier
	s_waitcnt lgkmcnt(0)
	v_mfma_f32_16x16x32_bf16 v[128:131], v[132:135], v[148:151], 0
	v_mfma_f32_16x16x32_bf16 v[124:127], v[140:143], v[148:151], 0
	v_mfma_f32_16x16x32_bf16 v[120:123], v[132:135], v[156:159], 0
	v_mfma_f32_16x16x32_bf16 v[116:119], v[140:143], v[156:159], 0
	v_mfma_f32_16x16x32_bf16 v[112:115], v[132:135], v[164:167], 0
	v_mfma_f32_16x16x32_bf16 v[108:111], v[140:143], v[164:167], 0
	v_mfma_f32_16x16x32_bf16 v[104:107], v[132:135], v[172:175], 0
	v_mfma_f32_16x16x32_bf16 v[100:103], v[140:143], v[172:175], 0
	v_mfma_f32_16x16x32_bf16 v[128:131], v[136:139], v[152:155], v[128:131]
	v_mfma_f32_16x16x32_bf16 v[124:127], v[144:147], v[152:155], v[124:127]
	v_mfma_f32_16x16x32_bf16 v[120:123], v[136:139], v[160:163], v[120:123]
	v_mfma_f32_16x16x32_bf16 v[116:119], v[144:147], v[160:163], v[116:119]
	v_mfma_f32_16x16x32_bf16 v[112:115], v[136:139], v[168:171], v[112:115]
	v_mfma_f32_16x16x32_bf16 v[108:111], v[144:147], v[168:171], v[108:111]
	v_mfma_f32_16x16x32_bf16 v[104:107], v[136:139], v[204:207], v[104:107]
	v_mfma_f32_16x16x32_bf16 v[100:103], v[144:147], v[204:207], v[100:103]
	s_barrier
	s_add_i32 s23, 0, 0x14000
	s_add_i32 s24, s25, s67
	s_mov_b32 m0, s24
	ds_read_b128 v[208:211], v216 offset:16384
	ds_read_b128 v[212:215], v216 offset:17408
	ds_read_b128 v[242:245], v216 offset:18432
	global_load_lds_dwordx4 v176, s[44:45]
	s_add_i32 m0, s24, 0x2000
	ds_read_b128 v[246:249], v216 offset:19456
	global_load_lds_dwordx4 v180, s[44:45]
	s_barrier
	s_waitcnt lgkmcnt(0)
	v_mfma_f32_16x16x32_bf16 v[64:67], v[208:211], v[148:151], 0
	v_mfma_f32_16x16x32_bf16 v[60:63], v[242:245], v[148:151], 0
	v_mfma_f32_16x16x32_bf16 v[56:59], v[208:211], v[156:159], 0
	v_mfma_f32_16x16x32_bf16 v[52:55], v[242:245], v[156:159], 0
	v_mfma_f32_16x16x32_bf16 v[48:51], v[208:211], v[164:167], 0
	v_mfma_f32_16x16x32_bf16 v[44:47], v[242:245], v[164:167], 0
	v_mfma_f32_16x16x32_bf16 v[40:43], v[208:211], v[172:175], 0
	v_mfma_f32_16x16x32_bf16 v[36:39], v[242:245], v[172:175], 0
	v_mfma_f32_16x16x32_bf16 v[64:67], v[212:215], v[152:155], v[64:67]
	v_mfma_f32_16x16x32_bf16 v[60:63], v[246:249], v[152:155], v[60:63]
	v_mfma_f32_16x16x32_bf16 v[56:59], v[212:215], v[160:163], v[56:59]
	v_mfma_f32_16x16x32_bf16 v[52:55], v[246:249], v[160:163], v[52:55]
	v_mfma_f32_16x16x32_bf16 v[48:51], v[212:215], v[168:171], v[48:51]
	v_mfma_f32_16x16x32_bf16 v[44:47], v[246:249], v[168:171], v[44:47]
	v_mfma_f32_16x16x32_bf16 v[40:43], v[212:215], v[204:207], v[40:43]
	v_mfma_f32_16x16x32_bf16 v[36:39], v[246:249], v[204:207], v[36:39]
	s_mov_b32 m0, s74
	s_barrier
	ds_read_b128 v[148:151], v240 offset:16384
	ds_read_b128 v[152:155], v240 offset:17408
	ds_read_b128 v[156:159], v240 offset:18432
	ds_read_b128 v[160:163], v240 offset:19456
	ds_read_b128 v[164:167], v240 offset:20480
	ds_read_b128 v[168:171], v240 offset:21504
	ds_read_b128 v[172:175], v240 offset:22528
	global_load_lds_dwordx4 v0, s[46:47]
	s_mov_b32 m0, s75
	ds_read_b128 v[204:207], v240 offset:23552
	global_load_lds_dwordx4 v178, s[46:47]
	s_barrier
	s_waitcnt lgkmcnt(0)
	v_mfma_f32_16x16x32_bf16 v[96:99], v[132:135], v[148:151], 0
	v_mfma_f32_16x16x32_bf16 v[92:95], v[140:143], v[148:151], 0
	v_mfma_f32_16x16x32_bf16 v[88:91], v[132:135], v[156:159], 0
	v_mfma_f32_16x16x32_bf16 v[84:87], v[140:143], v[156:159], 0
	v_mfma_f32_16x16x32_bf16 v[80:83], v[132:135], v[164:167], 0
	v_mfma_f32_16x16x32_bf16 v[76:79], v[140:143], v[164:167], 0
	v_mfma_f32_16x16x32_bf16 v[72:75], v[132:135], v[172:175], 0
	v_mfma_f32_16x16x32_bf16 v[68:71], v[140:143], v[172:175], 0
	v_mfma_f32_16x16x32_bf16 v[96:99], v[136:139], v[152:155], v[96:99]
	v_mfma_f32_16x16x32_bf16 v[92:95], v[144:147], v[152:155], v[92:95]
	v_mfma_f32_16x16x32_bf16 v[88:91], v[136:139], v[160:163], v[88:91]
	v_mfma_f32_16x16x32_bf16 v[84:87], v[144:147], v[160:163], v[84:87]
	v_mfma_f32_16x16x32_bf16 v[80:83], v[136:139], v[168:171], v[80:83]
	v_mfma_f32_16x16x32_bf16 v[76:79], v[144:147], v[168:171], v[76:79]
	v_mfma_f32_16x16x32_bf16 v[72:75], v[136:139], v[204:207], v[72:75]
	v_mfma_f32_16x16x32_bf16 v[68:71], v[144:147], v[204:207], v[68:71]
	s_barrier
	s_add_i32 s23, s23, s67
	s_mov_b32 m0, s23
	s_add_u32 s24, s44, 0x40000
	s_addc_u32 s25, s45, 0
	global_load_lds_dwordx4 v176, s[24:25]
	s_add_i32 m0, s23, 0x2000
	s_waitcnt vmcnt(5)
	global_load_lds_dwordx4 v180, s[24:25]
	s_barrier
	v_mfma_f32_16x16x32_bf16 v[32:35], v[208:211], v[148:151], 0
	v_mfma_f32_16x16x32_bf16 v[28:31], v[242:245], v[148:151], 0
	v_mfma_f32_16x16x32_bf16 v[24:27], v[208:211], v[156:159], 0
	v_mfma_f32_16x16x32_bf16 v[20:23], v[242:245], v[156:159], 0
	v_mfma_f32_16x16x32_bf16 v[16:19], v[208:211], v[164:167], 0
	v_mfma_f32_16x16x32_bf16 v[12:15], v[242:245], v[164:167], 0
	v_mfma_f32_16x16x32_bf16 v[8:11], v[208:211], v[172:175], 0
	v_mfma_f32_16x16x32_bf16 v[4:7], v[242:245], v[172:175], 0
	v_mfma_f32_16x16x32_bf16 v[32:35], v[212:215], v[152:155], v[32:35]
	v_mfma_f32_16x16x32_bf16 v[28:31], v[246:249], v[152:155], v[28:31]
	v_mfma_f32_16x16x32_bf16 v[24:27], v[212:215], v[160:163], v[24:27]
	v_mfma_f32_16x16x32_bf16 v[20:23], v[246:249], v[160:163], v[20:23]
	v_mfma_f32_16x16x32_bf16 v[16:19], v[212:215], v[168:171], v[16:19]
	v_mfma_f32_16x16x32_bf16 v[12:15], v[246:249], v[168:171], v[12:15]
	v_mfma_f32_16x16x32_bf16 v[8:11], v[212:215], v[204:207], v[8:11]
	v_mfma_f32_16x16x32_bf16 v[4:7], v[246:249], v[204:207], v[4:7]
	s_add_i32 s23, 0, 0x18000
	s_barrier
	ds_read_b128 v[132:135], v216 offset:32768
	ds_read_b128 v[136:139], v216 offset:33792
	ds_read_b128 v[140:143], v216 offset:34816
	ds_read_b128 v[144:147], v216 offset:35840
	s_add_u32 s24, s46, 0x40000
	s_addc_u32 s25, s47, 0
	s_mov_b32 m0, s82
	ds_read_b128 v[148:151], v240 offset:32768
	ds_read_b128 v[152:155], v240 offset:33792
	ds_read_b128 v[156:159], v240 offset:34816
	ds_read_b128 v[160:163], v240 offset:35840
	ds_read_b128 v[164:167], v240 offset:36864
	ds_read_b128 v[168:171], v240 offset:37888
	ds_read_b128 v[172:175], v240 offset:38912
	global_load_lds_dwordx4 v0, s[24:25]
	s_mov_b32 m0, s83
	ds_read_b128 v[204:207], v240 offset:39936
	global_load_lds_dwordx4 v178, s[24:25]
	s_waitcnt lgkmcnt(8)
	s_barrier
	s_waitcnt lgkmcnt(0)
	v_mfma_f32_16x16x32_bf16 v[128:131], v[132:135], v[148:151], v[128:131]
	v_mfma_f32_16x16x32_bf16 v[124:127], v[140:143], v[148:151], v[124:127]
	v_mfma_f32_16x16x32_bf16 v[120:123], v[132:135], v[156:159], v[120:123]
	v_mfma_f32_16x16x32_bf16 v[116:119], v[140:143], v[156:159], v[116:119]
	v_mfma_f32_16x16x32_bf16 v[112:115], v[132:135], v[164:167], v[112:115]
	v_mfma_f32_16x16x32_bf16 v[108:111], v[140:143], v[164:167], v[108:111]
	v_mfma_f32_16x16x32_bf16 v[104:107], v[132:135], v[172:175], v[104:107]
	v_mfma_f32_16x16x32_bf16 v[100:103], v[140:143], v[172:175], v[100:103]
	v_mfma_f32_16x16x32_bf16 v[128:131], v[136:139], v[152:155], v[128:131]
	v_mfma_f32_16x16x32_bf16 v[124:127], v[144:147], v[152:155], v[124:127]
	v_mfma_f32_16x16x32_bf16 v[120:123], v[136:139], v[160:163], v[120:123]
	v_mfma_f32_16x16x32_bf16 v[116:119], v[144:147], v[160:163], v[116:119]
	v_mfma_f32_16x16x32_bf16 v[112:115], v[136:139], v[168:171], v[112:115]
	v_mfma_f32_16x16x32_bf16 v[108:111], v[144:147], v[168:171], v[108:111]
	v_mfma_f32_16x16x32_bf16 v[104:107], v[136:139], v[204:207], v[104:107]
	v_mfma_f32_16x16x32_bf16 v[100:103], v[144:147], v[204:207], v[100:103]
	s_barrier
	s_add_i32 s26, 0, 0x1c000
	s_add_i32 s23, s23, s67
	s_mov_b32 m0, s23
	ds_read_b128 v[208:211], v216 offset:49152
	ds_read_b128 v[212:215], v216 offset:50176
	ds_read_b128 v[242:245], v216 offset:51200
	s_add_u32 s98, s44, 0x80
	s_addc_u32 s99, s45, 0
	global_load_lds_dwordx4 v176, s[98:99]
	s_add_i32 m0, s23, 0x2000
	ds_read_b128 v[246:249], v216 offset:52224
	global_load_lds_dwordx4 v180, s[98:99]
	s_barrier
	s_waitcnt lgkmcnt(0)
	v_mfma_f32_16x16x32_bf16 v[64:67], v[208:211], v[148:151], v[64:67]
	v_mfma_f32_16x16x32_bf16 v[60:63], v[242:245], v[148:151], v[60:63]
	v_mfma_f32_16x16x32_bf16 v[56:59], v[208:211], v[156:159], v[56:59]
	v_mfma_f32_16x16x32_bf16 v[52:55], v[242:245], v[156:159], v[52:55]
	v_mfma_f32_16x16x32_bf16 v[48:51], v[208:211], v[164:167], v[48:51]
	v_mfma_f32_16x16x32_bf16 v[44:47], v[242:245], v[164:167], v[44:47]
	v_mfma_f32_16x16x32_bf16 v[40:43], v[208:211], v[172:175], v[40:43]
	v_mfma_f32_16x16x32_bf16 v[36:39], v[242:245], v[172:175], v[36:39]
	v_mfma_f32_16x16x32_bf16 v[64:67], v[212:215], v[152:155], v[64:67]
	v_mfma_f32_16x16x32_bf16 v[60:63], v[246:249], v[152:155], v[60:63]
	v_mfma_f32_16x16x32_bf16 v[56:59], v[212:215], v[160:163], v[56:59]
	v_mfma_f32_16x16x32_bf16 v[52:55], v[246:249], v[160:163], v[52:55]
	v_mfma_f32_16x16x32_bf16 v[48:51], v[212:215], v[168:171], v[48:51]
	v_mfma_f32_16x16x32_bf16 v[44:47], v[246:249], v[168:171], v[44:47]
	v_mfma_f32_16x16x32_bf16 v[40:43], v[212:215], v[204:207], v[40:43]
	v_mfma_f32_16x16x32_bf16 v[36:39], v[246:249], v[204:207], v[36:39]
	s_mov_b32 m0, s48
	s_barrier
	ds_read_b128 v[148:151], v240 offset:49152
	ds_read_b128 v[152:155], v240 offset:50176
	ds_read_b128 v[156:159], v240 offset:51200
	ds_read_b128 v[160:163], v240 offset:52224
	ds_read_b128 v[164:167], v240 offset:53248
	ds_read_b128 v[168:171], v240 offset:54272
	ds_read_b128 v[172:175], v240 offset:55296
	s_add_u32 s98, s46, 0x80
	s_addc_u32 s99, s47, 0
	global_load_lds_dwordx4 v0, s[98:99]
	s_mov_b32 m0, s50
	ds_read_b128 v[204:207], v240 offset:56320
	global_load_lds_dwordx4 v178, s[98:99]
	s_barrier
	s_waitcnt lgkmcnt(0)
	v_mfma_f32_16x16x32_bf16 v[96:99], v[132:135], v[148:151], v[96:99]
	v_mfma_f32_16x16x32_bf16 v[92:95], v[140:143], v[148:151], v[92:95]
	v_mfma_f32_16x16x32_bf16 v[88:91], v[132:135], v[156:159], v[88:91]
	v_mfma_f32_16x16x32_bf16 v[84:87], v[140:143], v[156:159], v[84:87]
	v_mfma_f32_16x16x32_bf16 v[80:83], v[132:135], v[164:167], v[80:83]
	v_mfma_f32_16x16x32_bf16 v[76:79], v[140:143], v[164:167], v[76:79]
	v_mfma_f32_16x16x32_bf16 v[72:75], v[132:135], v[172:175], v[72:75]
	v_mfma_f32_16x16x32_bf16 v[68:71], v[140:143], v[172:175], v[68:71]
	v_mfma_f32_16x16x32_bf16 v[96:99], v[136:139], v[152:155], v[96:99]
	v_mfma_f32_16x16x32_bf16 v[92:95], v[144:147], v[152:155], v[92:95]
	v_mfma_f32_16x16x32_bf16 v[88:91], v[136:139], v[160:163], v[88:91]
	v_mfma_f32_16x16x32_bf16 v[84:87], v[144:147], v[160:163], v[84:87]
	v_mfma_f32_16x16x32_bf16 v[80:83], v[136:139], v[168:171], v[80:83]
	v_mfma_f32_16x16x32_bf16 v[76:79], v[144:147], v[168:171], v[76:79]
	v_mfma_f32_16x16x32_bf16 v[72:75], v[136:139], v[204:207], v[72:75]
	v_mfma_f32_16x16x32_bf16 v[68:71], v[144:147], v[204:207], v[68:71]
	s_barrier
	s_add_i32 s23, s26, s67
	s_mov_b32 m0, s23
	s_add_u32 s24, s44, 0x40080
	s_addc_u32 s25, s45, 0
	global_load_lds_dwordx4 v176, s[24:25]
	s_add_i32 m0, s23, 0x2000
	s_waitcnt vmcnt(5)
	global_load_lds_dwordx4 v180, s[24:25]
	s_barrier
	v_mfma_f32_16x16x32_bf16 v[32:35], v[208:211], v[148:151], v[32:35]
	v_mfma_f32_16x16x32_bf16 v[28:31], v[242:245], v[148:151], v[28:31]
	v_mfma_f32_16x16x32_bf16 v[24:27], v[208:211], v[156:159], v[24:27]
	v_mfma_f32_16x16x32_bf16 v[20:23], v[242:245], v[156:159], v[20:23]
	v_mfma_f32_16x16x32_bf16 v[16:19], v[208:211], v[164:167], v[16:19]
	v_mfma_f32_16x16x32_bf16 v[12:15], v[242:245], v[164:167], v[12:15]
	v_mfma_f32_16x16x32_bf16 v[8:11], v[208:211], v[172:175], v[8:11]
	v_mfma_f32_16x16x32_bf16 v[4:7], v[242:245], v[172:175], v[4:7]
	v_mfma_f32_16x16x32_bf16 v[32:35], v[212:215], v[152:155], v[32:35]
	v_mfma_f32_16x16x32_bf16 v[28:31], v[246:249], v[152:155], v[28:31]
	v_mfma_f32_16x16x32_bf16 v[24:27], v[212:215], v[160:163], v[24:27]
	v_mfma_f32_16x16x32_bf16 v[20:23], v[246:249], v[160:163], v[20:23]
	v_mfma_f32_16x16x32_bf16 v[16:19], v[212:215], v[168:171], v[16:19]
	v_mfma_f32_16x16x32_bf16 v[12:15], v[246:249], v[168:171], v[12:15]
	v_mfma_f32_16x16x32_bf16 v[8:11], v[212:215], v[204:207], v[8:11]
	v_mfma_f32_16x16x32_bf16 v[4:7], v[246:249], v[204:207], v[4:7]
	s_add_i32 s22, s22, 2
	s_add_u32 s0, s0, 0x100
	s_addc_u32 s1, s1, 0
	s_add_u32 s20, s20, 0x100
	s_addc_u32 s21, s21, 0
	s_cmp_gt_u32 s22, 13
	s_barrier
	s_cbranch_scc1 .Lpeel_out_427
